# baseline (speedup 1.0000x reference)
; #define STAGE(P, q) do { GLDS16(q[0], (unsigned char*)(P) + wid * 1024); GLDS16(q[1], (unsigned char*)(P) + wid * 1024 + 8192); \
;     q[0] += 128; q[1] += 128; asm volatile("" : "+v"(q[0]), "+v"(q[1])); } while (0)
; #define LDA(dst, b, h) _Pragma("unroll") for (int m = 0; m < 4; ++m) _Pragma("unroll") for (int k = 0; k < 2; ++k) \
;     dst[m][k] = *(const bf16x8*)((const unsigned char*)SA(b, h) + lds_byte1(wr * 64 + m * 16 + fr, k * 32 + fq * 8))
; #define LDB(dst, b, h) _Pragma("unroll") for (int n = 0; n < 2; ++n) _Pragma("unroll") for (int k = 0; k < 2; ++k) \
;     dst[n][k] = *(const bf16x8*)((const unsigned char*)SB(b, h) + lds_byte1(wc * 32 + n * 16 + fr, k * 32 + fq * 8))
; #define MMA(ai, bj, At_, Bt_) do { __builtin_amdgcn_s_setprio(1); \
;     _Pragma("unroll") for (int m = 0; m < 4; ++m) _Pragma("unroll") for (int n = 0; n < 2; ++n) _Pragma("unroll") for (int k = 0; k < 2; ++k) \
;       acc[ai][bj][m][n] = mfma16(At_[m][k], Bt_[n][k], acc[ai][bj][m][n]); \
;     __builtin_amdgcn_s_setprio(0); } while (0)
; #define WAIT_V(n) asm volatile("s_waitcnt vmcnt(" #n ")" ::: "memory")
; #define WAIT_L(n) asm volatile("s_waitcnt lgkmcnt(" #n ")" ::: "memory")
; #define BAR __builtin_amdgcn_s_barrier()
; #define SCHED __builtin_amdgcn_sched_barrier(0)
; DEV void gemm_tile(const u16* __restrict__ A, const u16* __restrict__ Bt, u16* __restrict__ C, int N, int K,
;                    int brow, int bcol, unsigned char* smem, int epi, const GateEpi& ge) {
;     ...
;   for (int t = 0; t < nt - 2; t += 2) {
;     LDB(B0, 0, 0); SCHED; LDA(At, 0, 0); STAGE(SA(1, 1), qA1);
;     WAIT_L(8); BAR; WAIT_L(0); MMA(0, 0, At, B0); BAR; SCHED;
;     LDB(B1, 0, 1); STAGE(SB(0, 0), qB0);
;     BAR; WAIT_L(0); MMA(0, 1, At, B1); BAR;
;     LDA(At, 0, 1); STAGE(SA(0, 0), qA0);
;     BAR; WAIT_L(0); MMA(1, 0, At, B0); BAR; SCHED;
;     STAGE(SB(0, 1), qB1);
;     WAIT_V(6); BAR; MMA(1, 1, At, B1); BAR;
;     LDB(B0, 1, 0); SCHED; LDA(At, 1, 0); STAGE(SA(0, 1), qA1);
;     WAIT_L(8); BAR; WAIT_L(0); MMA(0, 0, At, B0); BAR; SCHED;
;     LDB(B1, 1, 1); STAGE(SB(1, 0), qB0);
;     BAR; WAIT_L(0); MMA(0, 1, At, B1); BAR;
;     LDA(At, 1, 1); STAGE(SA(1, 0), qA0);
;     BAR; WAIT_L(0); MMA(1, 0, At, B0); BAR; SCHED;
;     STAGE(SB(1, 1), qB1);
;     WAIT_V(6); BAR; MMA(1, 1, At, B1); BAR;
;   }
.LBB0_634:
	ds_read_b128 v[156:159], v152
	ds_read_b128 v[180:183], v152 offset:1024
	ds_read_b128 v[184:187], v152 offset:256
	ds_read_b128 v[188:191], v152 offset:1280
	s_mov_b32 m0, s56
	v_add_u32_e32 v153, s53, v151
	v_add_u32_e32 v154, s54, v151
	v_add_u32_e32 v155, s55, v151
	ds_read_b128 v[192:195], v128
	ds_read_b128 v[196:199], v128 offset:1024
	ds_read_b128 v[200:203], v153
	ds_read_b128 v[204:207], v153 offset:1024
	ds_read_b128 v[208:211], v154
	ds_read_b128 v[212:215], v154 offset:1024
	ds_read_b128 v[216:219], v155
	ds_read_b128 v[220:223], v155 offset:1024
	global_load_lds_dwordx4 v[132:133], off
	s_mov_b32 m0, s52
	v_lshl_add_u64 v[236:237], v[132:133], 0, s[8:9]
	global_load_lds_dwordx4 v[134:135], off
	v_lshl_add_u64 v[238:239], v[134:135], 0, s[8:9]
	s_waitcnt lgkmcnt(8)
	s_barrier
	s_waitcnt lgkmcnt(0)
	s_setprio 1
	s_waitcnt lgkmcnt(0)
	v_mfma_f32_16x16x32_bf16 v[124:127], v[156:159], v[192:195], v[124:127]
	v_mfma_f32_16x16x32_bf16 v[120:123], v[184:187], v[192:195], v[120:123]
	v_mfma_f32_16x16x32_bf16 v[116:119], v[156:159], v[200:203], v[116:119]
	v_mfma_f32_16x16x32_bf16 v[112:115], v[184:187], v[200:203], v[112:115]
	v_mfma_f32_16x16x32_bf16 v[108:111], v[156:159], v[208:211], v[108:111]
	v_mfma_f32_16x16x32_bf16 v[104:107], v[184:187], v[208:211], v[104:107]
	v_mfma_f32_16x16x32_bf16 v[100:103], v[156:159], v[216:219], v[100:103]
	v_mfma_f32_16x16x32_bf16 v[96:99], v[184:187], v[216:219], v[96:99]
	v_mfma_f32_16x16x32_bf16 v[124:127], v[180:183], v[196:199], v[124:127]
	v_mfma_f32_16x16x32_bf16 v[120:123], v[188:191], v[196:199], v[120:123]
	v_mfma_f32_16x16x32_bf16 v[116:119], v[180:183], v[204:207], v[116:119]
	v_mfma_f32_16x16x32_bf16 v[112:115], v[188:191], v[204:207], v[112:115]
	v_mfma_f32_16x16x32_bf16 v[108:111], v[180:183], v[212:215], v[108:111]
	v_mfma_f32_16x16x32_bf16 v[104:107], v[188:191], v[212:215], v[104:107]
	v_mfma_f32_16x16x32_bf16 v[100:103], v[180:183], v[220:223], v[100:103]
	v_mfma_f32_16x16x32_bf16 v[96:99], v[188:191], v[220:223], v[96:99]
	s_setprio 0
	s_barrier
	s_mov_b32 m0, s4
	ds_read_b128 v[132:135], v150
	ds_read_b128 v[224:227], v150 offset:1024
	ds_read_b128 v[228:231], v150 offset:256
	ds_read_b128 v[232:235], v150 offset:1280
	global_load_lds_dwordx4 v[136:137], off
	s_mov_b32 m0, s5
	v_lshl_add_u64 v[240:241], v[136:137], 0, s[8:9]
	global_load_lds_dwordx4 v[138:139], off
	v_lshl_add_u64 v[242:243], v[138:139], 0, s[8:9]
	s_barrier
	s_waitcnt lgkmcnt(0)
	s_setprio 1
	s_waitcnt lgkmcnt(0)
	v_mfma_f32_16x16x32_bf16 v[84:87], v[132:135], v[192:195], v[84:87]
	v_mfma_f32_16x16x32_bf16 v[68:71], v[228:231], v[192:195], v[68:71]
	v_mfma_f32_16x16x32_bf16 v[52:55], v[132:135], v[200:203], v[52:55]
	v_mfma_f32_16x16x32_bf16 v[48:51], v[228:231], v[200:203], v[48:51]
	v_mfma_f32_16x16x32_bf16 v[44:47], v[132:135], v[208:211], v[44:47]
	v_mfma_f32_16x16x32_bf16 v[40:43], v[228:231], v[208:211], v[40:43]
	v_mfma_f32_16x16x32_bf16 v[36:39], v[132:135], v[216:219], v[36:39]
	v_mfma_f32_16x16x32_bf16 v[32:35], v[228:231], v[216:219], v[32:35]
	v_mfma_f32_16x16x32_bf16 v[84:87], v[224:227], v[196:199], v[84:87]
	v_mfma_f32_16x16x32_bf16 v[68:71], v[232:235], v[196:199], v[68:71]
	v_mfma_f32_16x16x32_bf16 v[52:55], v[224:227], v[204:207], v[52:55]
	v_mfma_f32_16x16x32_bf16 v[48:51], v[232:235], v[204:207], v[48:51]
	v_mfma_f32_16x16x32_bf16 v[44:47], v[224:227], v[212:215], v[44:47]
	v_mfma_f32_16x16x32_bf16 v[40:43], v[232:235], v[212:215], v[40:43]
	v_mfma_f32_16x16x32_bf16 v[36:39], v[224:227], v[220:223], v[36:39]
	v_mfma_f32_16x16x32_bf16 v[32:35], v[232:235], v[220:223], v[32:35]
	s_setprio 0
	s_mov_b32 m0, s1
	s_barrier
	ds_read_b128 v[136:139], v128 offset:16384
	ds_read_b128 v[192:195], v128 offset:17408
	ds_read_b128 v[196:199], v153 offset:16384
	ds_read_b128 v[200:203], v153 offset:17408
	ds_read_b128 v[204:207], v154 offset:16384
	ds_read_b128 v[208:211], v154 offset:17408
	ds_read_b128 v[212:215], v155 offset:16384
	ds_read_b128 v[216:219], v155 offset:17408
	global_load_lds_dwordx4 v[140:141], off
	s_mov_b32 m0, s6
	v_lshl_add_u64 v[244:245], v[140:141], 0, s[8:9]
	global_load_lds_dwordx4 v[142:143], off
	v_lshl_add_u64 v[246:247], v[142:143], 0, s[8:9]
	s_barrier
	s_waitcnt lgkmcnt(0)
	s_setprio 1
	s_waitcnt lgkmcnt(0)
	v_mfma_f32_16x16x32_bf16 v[28:31], v[156:159], v[136:139], v[28:31]
	v_mfma_f32_16x16x32_bf16 v[24:27], v[184:187], v[136:139], v[24:27]
	v_mfma_f32_16x16x32_bf16 v[20:23], v[156:159], v[196:199], v[20:23]
	v_mfma_f32_16x16x32_bf16 v[16:19], v[184:187], v[196:199], v[16:19]
	v_mfma_f32_16x16x32_bf16 v[12:15], v[156:159], v[204:207], v[12:15]
	v_mfma_f32_16x16x32_bf16 v[8:11], v[184:187], v[204:207], v[8:11]
	v_mfma_f32_16x16x32_bf16 v[4:7], v[156:159], v[212:215], v[4:7]
	v_mfma_f32_16x16x32_bf16 v[0:3], v[184:187], v[212:215], v[0:3]
	v_mfma_f32_16x16x32_bf16 v[28:31], v[180:183], v[192:195], v[28:31]
	v_mfma_f32_16x16x32_bf16 v[24:27], v[188:191], v[192:195], v[24:27]
	v_mfma_f32_16x16x32_bf16 v[20:23], v[180:183], v[200:203], v[20:23]
	v_mfma_f32_16x16x32_bf16 v[16:19], v[188:191], v[200:203], v[16:19]
	v_mfma_f32_16x16x32_bf16 v[12:15], v[180:183], v[208:211], v[12:15]
	v_mfma_f32_16x16x32_bf16 v[8:11], v[188:191], v[208:211], v[8:11]
	v_mfma_f32_16x16x32_bf16 v[4:7], v[180:183], v[216:219], v[4:7]
	v_mfma_f32_16x16x32_bf16 v[0:3], v[188:191], v[216:219], v[0:3]
	s_setprio 0
	s_barrier
	s_mov_b32 m0, s7
	v_lshl_add_u64 v[248:249], v[144:145], 0, s[8:9]
	global_load_lds_dwordx4 v[144:145], off
	s_mov_b32 m0, s35
	v_lshl_add_u64 v[250:251], v[146:147], 0, s[8:9]
	global_load_lds_dwordx4 v[146:147], off
	s_waitcnt vmcnt(6)
	s_barrier
; #define STAGE(P, q) do { GLDS16(q[0], (unsigned char*)(P) + wid * 1024); GLDS16(q[1], (unsigned char*)(P) + wid * 1024 + 8192); \
;     q[0] += 128; q[1] += 128; asm volatile("" : "+v"(q[0]), "+v"(q[1])); } while (0)
; #define LDA(dst, b, h) _Pragma("unroll") for (int m = 0; m < 4; ++m) _Pragma("unroll") for (int k = 0; k < 2; ++k) \
;     dst[m][k] = *(const bf16x8*)((const unsigned char*)SA(b, h) + lds_byte1(wr * 64 + m * 16 + fr, k * 32 + fq * 8))
; #define LDB(dst, b, h) _Pragma("unroll") for (int n = 0; n < 2; ++n) _Pragma("unroll") for (int k = 0; k < 2; ++k) \
;     dst[n][k] = *(const bf16x8*)((const unsigned char*)SB(b, h) + lds_byte1(wc * 32 + n * 16 + fr, k * 32 + fq * 8))
; #define MMA(ai, bj, At_, Bt_) do { __builtin_amdgcn_s_setprio(1); \
;     _Pragma("unroll") for (int m = 0; m < 4; ++m) _Pragma("unroll") for (int n = 0; n < 2; ++n) _Pragma("unroll") for (int k = 0; k < 2; ++k) \
;       acc[ai][bj][m][n] = mfma16(At_[m][k], Bt_[n][k], acc[ai][bj][m][n]); \
;     __builtin_amdgcn_s_setprio(0); } while (0)
; #define WAIT_V(n) asm volatile("s_waitcnt vmcnt(" #n ")" ::: "memory")
; #define WAIT_L(n) asm volatile("s_waitcnt lgkmcnt(" #n ")" ::: "memory")
; #define BAR __builtin_amdgcn_s_barrier()
; #define SCHED __builtin_amdgcn_sched_barrier(0)
; DEV void gemm_tile(const u16* __restrict__ A, const u16* __restrict__ Bt, u16* __restrict__ C, int N, int K,
;                    int brow, int bcol, unsigned char* smem, int epi, const GateEpi& ge) {
;     ...
;   for (int t = 0; t < nt - 2; t += 2) {
;     LDB(B0, 0, 0); SCHED; LDA(At, 0, 0); STAGE(SA(1, 1), qA1);
;     WAIT_L(8); BAR; WAIT_L(0); MMA(0, 0, At, B0); BAR; SCHED;
;     LDB(B1, 0, 1); STAGE(SB(0, 0), qB0);
;     BAR; WAIT_L(0); MMA(0, 1, At, B1); BAR;
;     LDA(At, 0, 1); STAGE(SA(0, 0), qA0);
;     BAR; WAIT_L(0); MMA(1, 0, At, B0); BAR; SCHED;
;     STAGE(SB(0, 1), qB1);
;     WAIT_V(6); BAR; MMA(1, 1, At, B1); BAR;
;     LDB(B0, 1, 0); SCHED; LDA(At, 1, 0); STAGE(SA(0, 1), qA1);
;     WAIT_L(8); BAR; WAIT_L(0); MMA(0, 0, At, B0); BAR; SCHED;
;     LDB(B1, 1, 1); STAGE(SB(1, 0), qB0);
;     BAR; WAIT_L(0); MMA(0, 1, At, B1); BAR;
;     LDA(At, 1, 1); STAGE(SA(1, 0), qA0);
;     BAR; WAIT_L(0); MMA(1, 0, At, B0); BAR; SCHED;
;     STAGE(SB(1, 1), qB1);
;     WAIT_V(6); BAR; MMA(1, 1, At, B1); BAR;
;   }
	s_setprio 1
	v_mfma_f32_16x16x32_bf16 v[56:59], v[132:135], v[136:139], v[56:59]
	v_mfma_f32_16x16x32_bf16 v[60:63], v[228:231], v[136:139], v[60:63]
	v_mfma_f32_16x16x32_bf16 v[64:67], v[132:135], v[196:199], v[64:67]
	v_mfma_f32_16x16x32_bf16 v[72:75], v[228:231], v[196:199], v[72:75]
	v_mfma_f32_16x16x32_bf16 v[76:79], v[132:135], v[204:207], v[76:79]
	v_mfma_f32_16x16x32_bf16 v[80:83], v[228:231], v[204:207], v[80:83]
	v_mfma_f32_16x16x32_bf16 v[88:91], v[132:135], v[212:215], v[88:91]
	v_mfma_f32_16x16x32_bf16 v[92:95], v[228:231], v[212:215], v[92:95]
	v_mfma_f32_16x16x32_bf16 v[56:59], v[224:227], v[192:195], v[56:59]
	v_mfma_f32_16x16x32_bf16 v[60:63], v[232:235], v[192:195], v[60:63]
	v_mfma_f32_16x16x32_bf16 v[64:67], v[224:227], v[200:203], v[64:67]
	v_mfma_f32_16x16x32_bf16 v[72:75], v[232:235], v[200:203], v[72:75]
	v_mfma_f32_16x16x32_bf16 v[76:79], v[224:227], v[208:211], v[76:79]
	v_mfma_f32_16x16x32_bf16 v[80:83], v[232:235], v[208:211], v[80:83]
	v_mfma_f32_16x16x32_bf16 v[88:91], v[224:227], v[216:219], v[88:91]
	v_mfma_f32_16x16x32_bf16 v[92:95], v[232:235], v[216:219], v[92:95]
	s_setprio 0
	s_barrier
	ds_read_b128 v[144:147], v149
	ds_read_b128 v[156:159], v149 offset:1024
	ds_read_b128 v[180:183], v149 offset:256
	ds_read_b128 v[184:187], v149 offset:1280
	s_mov_b32 m0, s41
	ds_read_b128 v[140:143], v128 offset:32768
	ds_read_b128 v[188:191], v128 offset:33792
	ds_read_b128 v[192:195], v153 offset:32768
	ds_read_b128 v[196:199], v153 offset:33792
	ds_read_b128 v[200:203], v154 offset:32768
	ds_read_b128 v[204:207], v154 offset:33792
	ds_read_b128 v[208:211], v155 offset:32768
	ds_read_b128 v[212:215], v155 offset:33792
	global_load_lds_dwordx4 v[236:237], off
	s_mov_b32 m0, vcc_lo
	v_lshl_add_u64 v[132:133], v[236:237], 0, s[8:9]
	global_load_lds_dwordx4 v[238:239], off
	v_lshl_add_u64 v[134:135], v[238:239], 0, s[8:9]
	s_waitcnt lgkmcnt(8)
	s_barrier
	s_waitcnt lgkmcnt(0)
	s_setprio 1
	s_waitcnt lgkmcnt(0)
	v_mfma_f32_16x16x32_bf16 v[124:127], v[144:147], v[140:143], v[124:127]
	v_mfma_f32_16x16x32_bf16 v[120:123], v[180:183], v[140:143], v[120:123]
	v_mfma_f32_16x16x32_bf16 v[116:119], v[144:147], v[192:195], v[116:119]
	v_mfma_f32_16x16x32_bf16 v[112:115], v[180:183], v[192:195], v[112:115]
	v_mfma_f32_16x16x32_bf16 v[108:111], v[144:147], v[200:203], v[108:111]
	v_mfma_f32_16x16x32_bf16 v[104:107], v[180:183], v[200:203], v[104:107]
	v_mfma_f32_16x16x32_bf16 v[100:103], v[144:147], v[208:211], v[100:103]
	v_mfma_f32_16x16x32_bf16 v[96:99], v[180:183], v[208:211], v[96:99]
	v_mfma_f32_16x16x32_bf16 v[124:127], v[156:159], v[188:191], v[124:127]
	v_mfma_f32_16x16x32_bf16 v[120:123], v[184:187], v[188:191], v[120:123]
	v_mfma_f32_16x16x32_bf16 v[116:119], v[156:159], v[196:199], v[116:119]
	v_mfma_f32_16x16x32_bf16 v[112:115], v[184:187], v[196:199], v[112:115]
	v_mfma_f32_16x16x32_bf16 v[108:111], v[156:159], v[204:207], v[108:111]
	v_mfma_f32_16x16x32_bf16 v[104:107], v[184:187], v[204:207], v[104:107]
	v_mfma_f32_16x16x32_bf16 v[100:103], v[156:159], v[212:215], v[100:103]
	v_mfma_f32_16x16x32_bf16 v[96:99], v[184:187], v[212:215], v[96:99]
	s_setprio 0
	s_barrier
	s_mov_b32 m0, vcc_hi
	ds_read_b128 v[216:219], v148
	ds_read_b128 v[220:223], v148 offset:1024
	ds_read_b128 v[224:227], v148 offset:256
	ds_read_b128 v[228:231], v148 offset:1280
	global_load_lds_dwordx4 v[240:241], off
	s_mov_b32 m0, s28
	v_lshl_add_u64 v[136:137], v[240:241], 0, s[8:9]
	global_load_lds_dwordx4 v[242:243], off
	v_lshl_add_u64 v[138:139], v[242:243], 0, s[8:9]
	s_barrier
	s_waitcnt lgkmcnt(0)
	s_setprio 1
	s_waitcnt lgkmcnt(0)
	v_mfma_f32_16x16x32_bf16 v[84:87], v[216:219], v[140:143], v[84:87]
	v_mfma_f32_16x16x32_bf16 v[68:71], v[224:227], v[140:143], v[68:71]
	v_mfma_f32_16x16x32_bf16 v[52:55], v[216:219], v[192:195], v[52:55]
	v_mfma_f32_16x16x32_bf16 v[48:51], v[224:227], v[192:195], v[48:51]
	v_mfma_f32_16x16x32_bf16 v[44:47], v[216:219], v[200:203], v[44:47]
	v_mfma_f32_16x16x32_bf16 v[40:43], v[224:227], v[200:203], v[40:43]
	v_mfma_f32_16x16x32_bf16 v[36:39], v[216:219], v[208:211], v[36:39]
	v_mfma_f32_16x16x32_bf16 v[32:35], v[224:227], v[208:211], v[32:35]
	v_mfma_f32_16x16x32_bf16 v[84:87], v[220:223], v[188:191], v[84:87]
	v_mfma_f32_16x16x32_bf16 v[68:71], v[228:231], v[188:191], v[68:71]
	v_mfma_f32_16x16x32_bf16 v[52:55], v[220:223], v[196:199], v[52:55]
	v_mfma_f32_16x16x32_bf16 v[48:51], v[228:231], v[196:199], v[48:51]
	v_mfma_f32_16x16x32_bf16 v[44:47], v[220:223], v[204:207], v[44:47]
	v_mfma_f32_16x16x32_bf16 v[40:43], v[228:231], v[204:207], v[40:43]
	v_mfma_f32_16x16x32_bf16 v[36:39], v[220:223], v[212:215], v[36:39]
	v_mfma_f32_16x16x32_bf16 v[32:35], v[228:231], v[212:215], v[32:35]
	s_setprio 0
	s_mov_b32 m0, s94
	s_barrier
	ds_read_b128 v[188:191], v128 offset:49152
	ds_read_b128 v[192:195], v128 offset:50176
	ds_read_b128 v[196:199], v153 offset:49152
	ds_read_b128 v[200:203], v153 offset:50176
	ds_read_b128 v[204:207], v154 offset:49152
	ds_read_b128 v[208:211], v154 offset:50176
	ds_read_b128 v[212:215], v155 offset:49152
	ds_read_b128 v[232:235], v155 offset:50176
	global_load_lds_dwordx4 v[244:245], off
	s_mov_b32 m0, s95
	v_lshl_add_u64 v[140:141], v[244:245], 0, s[8:9]
	global_load_lds_dwordx4 v[246:247], off
	v_lshl_add_u64 v[142:143], v[246:247], 0, s[8:9]
	s_barrier
; #define STAGE(P, q) do { GLDS16(q[0], (unsigned char*)(P) + wid * 1024); GLDS16(q[1], (unsigned char*)(P) + wid * 1024 + 8192); \
;     q[0] += 128; q[1] += 128; asm volatile("" : "+v"(q[0]), "+v"(q[1])); } while (0)
; #define LDA(dst, b, h) _Pragma("unroll") for (int m = 0; m < 4; ++m) _Pragma("unroll") for (int k = 0; k < 2; ++k) \
;     dst[m][k] = *(const bf16x8*)((const unsigned char*)SA(b, h) + lds_byte1(wr * 64 + m * 16 + fr, k * 32 + fq * 8))
; #define WAIT_V(n) asm volatile("s_waitcnt vmcnt(" #n ")" ::: "memory")
; DEV void gemm_tile(const u16* __restrict__ A, const u16* __restrict__ Bt, u16* __restrict__ C, int N, int K,
;                    int brow, int bcol, unsigned char* smem, int epi, const GateEpi& ge) {
;     ...
;   for (int t = 0; t < nt - 2; t += 2) {
;     LDB(B0, 0, 0); SCHED; LDA(At, 0, 0); STAGE(SA(1, 1), qA1);
;     WAIT_L(8); BAR; WAIT_L(0); MMA(0, 0, At, B0); BAR; SCHED;
;     LDB(B1, 0, 1); STAGE(SB(0, 0), qB0);
;     BAR; WAIT_L(0); MMA(0, 1, At, B1); BAR;
;     LDA(At, 0, 1); STAGE(SA(0, 0), qA0);
;     BAR; WAIT_L(0); MMA(1, 0, At, B0); BAR; SCHED;
;     STAGE(SB(0, 1), qB1);
;     WAIT_V(6); BAR; MMA(1, 1, At, B1); BAR;
;     LDB(B0, 1, 0); SCHED; LDA(At, 1, 0); STAGE(SA(0, 1), qA1);
;     WAIT_L(8); BAR; WAIT_L(0); MMA(0, 0, At, B0); BAR; SCHED;
;     LDB(B1, 1, 1); STAGE(SB(1, 0), qB0);
;     BAR; WAIT_L(0); MMA(0, 1, At, B1); BAR;
;     LDA(At, 1, 1); STAGE(SA(1, 0), qA0);
;     BAR; WAIT_L(0); MMA(1, 0, At, B0); BAR; SCHED;
;     STAGE(SB(1, 1), qB1);
;     WAIT_V(6); BAR; MMA(1, 1, At, B1); BAR;
;   }
;   { LDB(B0, 0, 0); LDA(At, 0, 0); STAGE(SA(1, 1), qA1);
;     BAR; WAIT_L(0); MMA(0, 0, At, B0); BAR;
;     LDB(B1, 0, 1); BAR; WAIT_L(0); MMA(0, 1, At, B1); BAR;
;     LDA(At, 0, 1); WAIT_V(4); BAR; WAIT_L(0); MMA(1, 0, At, B0); MMA(1, 1, At, B1); BAR; }
;   { LDB(B0, 1, 0); LDA(At, 1, 0); WAIT_V(2); BAR; WAIT_L(0); MMA(0, 0, At, B0); BAR;
;     LDB(B1, 1, 1); WAIT_V(0); BAR; WAIT_L(0); MMA(0, 1, At, B1); BAR;
;     LDA(At, 1, 1); BAR; WAIT_L(0); MMA(1, 0, At, B0); MMA(1, 1, At, B1); BAR; }
;     ...
;     const int pm = brow >> 8, pn = bcol >> 8;
;     float w0[2], w1[2], w2[2], bs[2];
; #pragma unroll
;     for (int n = 0; n < 2; ++n) {
;       const int cg = pn * 128 + wc * 32 + n * 16 + fr2;
;       w0[n] = ge.cw[cg]; w1[n] = ge.cw[DFF + cg]; w2[n] = ge.cw[2 * DFF + cg]; bs[n] = ge.cb[cg];
;     }
	s_waitcnt lgkmcnt(0)
	s_setprio 1
	s_waitcnt lgkmcnt(0)
	v_mfma_f32_16x16x32_bf16 v[28:31], v[144:147], v[188:191], v[28:31]
	v_mfma_f32_16x16x32_bf16 v[24:27], v[180:183], v[188:191], v[24:27]
	v_mfma_f32_16x16x32_bf16 v[20:23], v[144:147], v[196:199], v[20:23]
	v_mfma_f32_16x16x32_bf16 v[16:19], v[180:183], v[196:199], v[16:19]
	v_mfma_f32_16x16x32_bf16 v[12:15], v[144:147], v[204:207], v[12:15]
	v_mfma_f32_16x16x32_bf16 v[8:11], v[180:183], v[204:207], v[8:11]
	v_mfma_f32_16x16x32_bf16 v[4:7], v[144:147], v[212:215], v[4:7]
	v_mfma_f32_16x16x32_bf16 v[0:3], v[180:183], v[212:215], v[0:3]
	v_mfma_f32_16x16x32_bf16 v[28:31], v[156:159], v[192:195], v[28:31]
	v_mfma_f32_16x16x32_bf16 v[24:27], v[184:187], v[192:195], v[24:27]
	v_mfma_f32_16x16x32_bf16 v[20:23], v[156:159], v[200:203], v[20:23]
	v_mfma_f32_16x16x32_bf16 v[16:19], v[184:187], v[200:203], v[16:19]
	v_mfma_f32_16x16x32_bf16 v[12:15], v[156:159], v[208:211], v[12:15]
	v_mfma_f32_16x16x32_bf16 v[8:11], v[184:187], v[208:211], v[8:11]
	v_mfma_f32_16x16x32_bf16 v[4:7], v[156:159], v[232:235], v[4:7]
	v_mfma_f32_16x16x32_bf16 v[0:3], v[184:187], v[232:235], v[0:3]
	s_setprio 0
	s_barrier
	s_mov_b32 m0, s62
	v_lshl_add_u64 v[144:145], v[248:249], 0, s[8:9]
	global_load_lds_dwordx4 v[248:249], off
	s_mov_b32 m0, s63
	v_lshl_add_u64 v[146:147], v[250:251], 0, s[8:9]
	global_load_lds_dwordx4 v[250:251], off
	s_waitcnt vmcnt(6)
	s_barrier
	s_setprio 1
	v_mfma_f32_16x16x32_bf16 v[56:59], v[216:219], v[188:191], v[56:59]
	v_mfma_f32_16x16x32_bf16 v[60:63], v[224:227], v[188:191], v[60:63]
	v_mfma_f32_16x16x32_bf16 v[64:67], v[216:219], v[196:199], v[64:67]
	v_mfma_f32_16x16x32_bf16 v[72:75], v[224:227], v[196:199], v[72:75]
	v_mfma_f32_16x16x32_bf16 v[76:79], v[216:219], v[204:207], v[76:79]
	v_mfma_f32_16x16x32_bf16 v[80:83], v[224:227], v[204:207], v[80:83]
	v_mfma_f32_16x16x32_bf16 v[88:91], v[216:219], v[212:215], v[88:91]
	v_mfma_f32_16x16x32_bf16 v[92:95], v[224:227], v[212:215], v[92:95]
	v_mfma_f32_16x16x32_bf16 v[56:59], v[220:223], v[192:195], v[56:59]
	v_mfma_f32_16x16x32_bf16 v[60:63], v[228:231], v[192:195], v[60:63]
	v_mfma_f32_16x16x32_bf16 v[64:67], v[220:223], v[200:203], v[64:67]
	v_mfma_f32_16x16x32_bf16 v[72:75], v[228:231], v[200:203], v[72:75]
	v_mfma_f32_16x16x32_bf16 v[76:79], v[220:223], v[208:211], v[76:79]
	v_mfma_f32_16x16x32_bf16 v[80:83], v[228:231], v[208:211], v[80:83]
	v_mfma_f32_16x16x32_bf16 v[88:91], v[220:223], v[232:235], v[88:91]
	v_mfma_f32_16x16x32_bf16 v[92:95], v[228:231], v[232:235], v[92:95]
	s_setprio 0
	s_add_i32 s57, s57, 2
	s_cmp_lt_i32 s57, s45
	s_barrier
	s_cbranch_scc1 .LBB0_634
	s_add_i32 s0, s48, s33
	s_cmp_lt_i32 s0, s43
	s_cbranch_scc1 .Lg_last
	ds_read_b128 v[156:159], v152
	ds_read_b128 v[180:183], v152 offset:1024
	ds_read_b128 v[184:187], v152 offset:256
	ds_read_b128 v[188:191], v152 offset:1280
	s_mov_b32 m0, s56
	v_add_u32_e32 v153, s53, v151
	v_add_u32_e32 v154, s54, v151
	v_add_u32_e32 v155, s55, v151
	ds_read_b128 v[192:195], v128
	ds_read_b128 v[196:199], v128 offset:1024
	ds_read_b128 v[200:203], v153
	ds_read_b128 v[204:207], v153 offset:1024
	ds_read_b128 v[208:211], v154
	ds_read_b128 v[212:215], v154 offset:1024
	ds_read_b128 v[216:219], v155
	ds_read_b128 v[220:223], v155 offset:1024
	global_load_lds_dwordx4 v[132:133], off
	s_mov_b32 m0, s52
	v_lshl_add_u64 v[236:237], v[132:133], 0, s[8:9]
	global_load_lds_dwordx4 v[134:135], off
	v_lshl_add_u64 v[238:239], v[134:135], 0, s[8:9]
	s_andn2_b64 s[54:55], exec, s[2:3]
	s_cmp_lg_u64 s[54:55], 0
	s_cbranch_scc1 .Lwdma_skip_drain
	v_readlane_b32 s54, v252, 38
	v_readlane_b32 s55, v252, 39
	v_readlane_b32 s58, v252, 40
	v_readlane_b32 s59, v252, 41
	s_lshl_b32 s0, s47, 6
	s_and_b32 s0, s0, 0xfffffe00
	s_lshl_b32 s53, s50, 7
	s_add_i32 s0, s0, s53
	v_mbcnt_lo_u32_b32 v224, -1, 0
	v_mbcnt_hi_u32_b32 v224, -1, v224
	v_and_b32_e32 v230, 7, v224
	v_lshlrev_b32_e32 v230, 4, v230
	v_add_u32_e32 v230, s0, v230
	v_bfe_u32 v226, v224, 3, 2
	v_mul_u32_u24_e32 v228, 0x5800, v226
	v_add_u32_e32 v228, v228, v230
	v_mov_b32_e32 v229, 0
	v_mov_b32_e32 v231, 0
	v_lshl_add_u64 v[232:233], s[54:55], 0, v[228:229]
	v_lshl_add_u64 v[234:235], s[58:59], 0, v[230:231]
	v_cmp_eq_u32_e64 s[54:55], 3, v226
	s_add_i32 s0, s1, 0x21000
	s_mov_b32 m0, s0
	v_cndmask_b32_e64 v232, v232, v234, s[54:55]
	v_cndmask_b32_e64 v233, v233, v235, s[54:55]
	s_nop 1
	global_load_lds_dwordx4 v[232:233], off
; #define STAGE(P, q) do { GLDS16(q[0], (unsigned char*)(P) + wid * 1024); GLDS16(q[1], (unsigned char*)(P) + wid * 1024 + 8192); \
;     q[0] += 128; q[1] += 128; asm volatile("" : "+v"(q[0]), "+v"(q[1])); } while (0)
; #define LDA(dst, b, h) _Pragma("unroll") for (int m = 0; m < 4; ++m) _Pragma("unroll") for (int k = 0; k < 2; ++k) \
;     dst[m][k] = *(const bf16x8*)((const unsigned char*)SA(b, h) + lds_byte1(wr * 64 + m * 16 + fr, k * 32 + fq * 8))
; #define LDB(dst, b, h) _Pragma("unroll") for (int n = 0; n < 2; ++n) _Pragma("unroll") for (int k = 0; k < 2; ++k) \
;     dst[n][k] = *(const bf16x8*)((const unsigned char*)SB(b, h) + lds_byte1(wc * 32 + n * 16 + fr, k * 32 + fq * 8))
; #define MMA(ai, bj, At_, Bt_) do { __builtin_amdgcn_s_setprio(1); \
;     _Pragma("unroll") for (int m = 0; m < 4; ++m) _Pragma("unroll") for (int n = 0; n < 2; ++n) _Pragma("unroll") for (int k = 0; k < 2; ++k) \
;       acc[ai][bj][m][n] = mfma16(At_[m][k], Bt_[n][k], acc[ai][bj][m][n]); \
;     __builtin_amdgcn_s_setprio(0); } while (0)
; #define WAIT_V(n) asm volatile("s_waitcnt vmcnt(" #n ")" ::: "memory")
; #define WAIT_L(n) asm volatile("s_waitcnt lgkmcnt(" #n ")" ::: "memory")
; #define BAR __builtin_amdgcn_s_barrier()
; DEV void gemm_tile(const u16* __restrict__ A, const u16* __restrict__ Bt, u16* __restrict__ C, int N, int K,
;                    int brow, int bcol, unsigned char* smem, int epi, const GateEpi& ge) {
;     ...
;   { LDB(B0, 0, 0); LDA(At, 0, 0); STAGE(SA(1, 1), qA1);
;     BAR; WAIT_L(0); MMA(0, 0, At, B0); BAR;
;     LDB(B1, 0, 1); BAR; WAIT_L(0); MMA(0, 1, At, B1); BAR;
;     LDA(At, 0, 1); WAIT_V(4); BAR; WAIT_L(0); MMA(1, 0, At, B0); MMA(1, 1, At, B1); BAR; }
;   { LDB(B0, 1, 0); LDA(At, 1, 0); WAIT_V(2); BAR; WAIT_L(0); MMA(0, 0, At, B0); BAR;
;     LDB(B1, 1, 1); WAIT_V(0); BAR; WAIT_L(0); MMA(0, 1, At, B1); BAR;
;     LDA(At, 1, 1); BAR; WAIT_L(0); MMA(1, 0, At, B0); MMA(1, 1, At, B1); BAR; }
.Lwdma_skip_drain:
	s_waitcnt lgkmcnt(8)
	s_barrier
	s_waitcnt lgkmcnt(0)
	s_setprio 1
	s_waitcnt lgkmcnt(0)
	v_mfma_f32_16x16x32_bf16 v[124:127], v[156:159], v[192:195], v[124:127]
	v_mfma_f32_16x16x32_bf16 v[120:123], v[184:187], v[192:195], v[120:123]
	v_mfma_f32_16x16x32_bf16 v[116:119], v[156:159], v[200:203], v[116:119]
	v_mfma_f32_16x16x32_bf16 v[112:115], v[184:187], v[200:203], v[112:115]
	v_mfma_f32_16x16x32_bf16 v[108:111], v[156:159], v[208:211], v[108:111]
	v_mfma_f32_16x16x32_bf16 v[104:107], v[184:187], v[208:211], v[104:107]
	v_mfma_f32_16x16x32_bf16 v[100:103], v[156:159], v[216:219], v[100:103]
	v_mfma_f32_16x16x32_bf16 v[96:99], v[184:187], v[216:219], v[96:99]
	v_mfma_f32_16x16x32_bf16 v[124:127], v[180:183], v[196:199], v[124:127]
	v_mfma_f32_16x16x32_bf16 v[120:123], v[188:191], v[196:199], v[120:123]
	v_mfma_f32_16x16x32_bf16 v[116:119], v[180:183], v[204:207], v[116:119]
	v_mfma_f32_16x16x32_bf16 v[112:115], v[188:191], v[204:207], v[112:115]
	v_mfma_f32_16x16x32_bf16 v[108:111], v[180:183], v[212:215], v[108:111]
	v_mfma_f32_16x16x32_bf16 v[104:107], v[188:191], v[212:215], v[104:107]
	v_mfma_f32_16x16x32_bf16 v[100:103], v[180:183], v[220:223], v[100:103]
	v_mfma_f32_16x16x32_bf16 v[96:99], v[188:191], v[220:223], v[96:99]
	s_setprio 0
	s_barrier
	s_mov_b32 m0, s4
	ds_read_b128 v[132:135], v150
	ds_read_b128 v[224:227], v150 offset:1024
	ds_read_b128 v[228:231], v150 offset:256
	ds_read_b128 v[232:235], v150 offset:1280
	s_mov_b32 m0, s5
	v_lshl_add_u64 v[240:241], v[136:137], 0, s[8:9]
	v_lshl_add_u64 v[242:243], v[138:139], 0, s[8:9]
	s_barrier
	s_waitcnt lgkmcnt(0)
	s_setprio 1
	s_waitcnt lgkmcnt(0)
	v_mfma_f32_16x16x32_bf16 v[84:87], v[132:135], v[192:195], v[84:87]
	v_mfma_f32_16x16x32_bf16 v[68:71], v[228:231], v[192:195], v[68:71]
	v_mfma_f32_16x16x32_bf16 v[52:55], v[132:135], v[200:203], v[52:55]
	v_mfma_f32_16x16x32_bf16 v[48:51], v[228:231], v[200:203], v[48:51]
	v_mfma_f32_16x16x32_bf16 v[44:47], v[132:135], v[208:211], v[44:47]
	v_mfma_f32_16x16x32_bf16 v[40:43], v[228:231], v[208:211], v[40:43]
	v_mfma_f32_16x16x32_bf16 v[36:39], v[132:135], v[216:219], v[36:39]
	v_mfma_f32_16x16x32_bf16 v[32:35], v[228:231], v[216:219], v[32:35]
	v_mfma_f32_16x16x32_bf16 v[84:87], v[224:227], v[196:199], v[84:87]
	v_mfma_f32_16x16x32_bf16 v[68:71], v[232:235], v[196:199], v[68:71]
	v_mfma_f32_16x16x32_bf16 v[52:55], v[224:227], v[204:207], v[52:55]
	v_mfma_f32_16x16x32_bf16 v[48:51], v[232:235], v[204:207], v[48:51]
	v_mfma_f32_16x16x32_bf16 v[44:47], v[224:227], v[212:215], v[44:47]
	v_mfma_f32_16x16x32_bf16 v[40:43], v[232:235], v[212:215], v[40:43]
	v_mfma_f32_16x16x32_bf16 v[36:39], v[224:227], v[220:223], v[36:39]
	v_mfma_f32_16x16x32_bf16 v[32:35], v[232:235], v[220:223], v[32:35]
	s_setprio 0
	s_mov_b32 m0, s1
	s_barrier
	ds_read_b128 v[136:139], v128 offset:16384
	ds_read_b128 v[192:195], v128 offset:17408
	ds_read_b128 v[196:199], v153 offset:16384
	ds_read_b128 v[200:203], v153 offset:17408
	ds_read_b128 v[204:207], v154 offset:16384
	ds_read_b128 v[208:211], v154 offset:17408
	ds_read_b128 v[212:215], v155 offset:16384
	ds_read_b128 v[216:219], v155 offset:17408
	s_mov_b32 m0, s6
	v_lshl_add_u64 v[244:245], v[140:141], 0, s[8:9]
	v_lshl_add_u64 v[246:247], v[142:143], 0, s[8:9]
	s_barrier
	s_waitcnt lgkmcnt(0)
	s_setprio 1
	s_waitcnt lgkmcnt(0)
	v_mfma_f32_16x16x32_bf16 v[28:31], v[156:159], v[136:139], v[28:31]
	v_mfma_f32_16x16x32_bf16 v[24:27], v[184:187], v[136:139], v[24:27]
	v_mfma_f32_16x16x32_bf16 v[20:23], v[156:159], v[196:199], v[20:23]
	v_mfma_f32_16x16x32_bf16 v[16:19], v[184:187], v[196:199], v[16:19]
	v_mfma_f32_16x16x32_bf16 v[12:15], v[156:159], v[204:207], v[12:15]
	v_mfma_f32_16x16x32_bf16 v[8:11], v[184:187], v[204:207], v[8:11]
	v_mfma_f32_16x16x32_bf16 v[4:7], v[156:159], v[212:215], v[4:7]
	v_mfma_f32_16x16x32_bf16 v[0:3], v[184:187], v[212:215], v[0:3]
	v_mfma_f32_16x16x32_bf16 v[28:31], v[180:183], v[192:195], v[28:31]
	v_mfma_f32_16x16x32_bf16 v[24:27], v[188:191], v[192:195], v[24:27]
	v_mfma_f32_16x16x32_bf16 v[20:23], v[180:183], v[200:203], v[20:23]
	v_mfma_f32_16x16x32_bf16 v[16:19], v[188:191], v[200:203], v[16:19]
	v_mfma_f32_16x16x32_bf16 v[12:15], v[180:183], v[208:211], v[12:15]
	v_mfma_f32_16x16x32_bf16 v[8:11], v[188:191], v[208:211], v[8:11]
	v_mfma_f32_16x16x32_bf16 v[4:7], v[180:183], v[216:219], v[4:7]
	v_mfma_f32_16x16x32_bf16 v[0:3], v[188:191], v[216:219], v[0:3]
	s_setprio 0
	s_barrier
	s_mov_b32 m0, s7
	v_lshl_add_u64 v[248:249], v[144:145], 0, s[8:9]
	s_mov_b32 m0, s35
	v_lshl_add_u64 v[250:251], v[146:147], 0, s[8:9]
	s_waitcnt vmcnt(0)
	s_barrier
	s_setprio 1
	v_mfma_f32_16x16x32_bf16 v[56:59], v[132:135], v[136:139], v[56:59]
	v_mfma_f32_16x16x32_bf16 v[60:63], v[228:231], v[136:139], v[60:63]
	v_mfma_f32_16x16x32_bf16 v[64:67], v[132:135], v[196:199], v[64:67]
	v_mfma_f32_16x16x32_bf16 v[72:75], v[228:231], v[196:199], v[72:75]
	v_mfma_f32_16x16x32_bf16 v[76:79], v[132:135], v[204:207], v[76:79]
	v_mfma_f32_16x16x32_bf16 v[80:83], v[228:231], v[204:207], v[80:83]
	v_mfma_f32_16x16x32_bf16 v[88:91], v[132:135], v[212:215], v[88:91]
	v_mfma_f32_16x16x32_bf16 v[92:95], v[228:231], v[212:215], v[92:95]
	v_mfma_f32_16x16x32_bf16 v[56:59], v[224:227], v[192:195], v[56:59]
	v_mfma_f32_16x16x32_bf16 v[60:63], v[232:235], v[192:195], v[60:63]
	v_mfma_f32_16x16x32_bf16 v[64:67], v[224:227], v[200:203], v[64:67]
	v_mfma_f32_16x16x32_bf16 v[72:75], v[232:235], v[200:203], v[72:75]
	v_mfma_f32_16x16x32_bf16 v[76:79], v[224:227], v[208:211], v[76:79]
	v_mfma_f32_16x16x32_bf16 v[80:83], v[232:235], v[208:211], v[80:83]
	v_mfma_f32_16x16x32_bf16 v[88:91], v[224:227], v[216:219], v[88:91]
	v_mfma_f32_16x16x32_bf16 v[92:95], v[232:235], v[216:219], v[92:95]
	s_setprio 0
	s_barrier
; #define STAGE(P, q) do { GLDS16(q[0], (unsigned char*)(P) + wid * 1024); GLDS16(q[1], (unsigned char*)(P) + wid * 1024 + 8192); \
;     q[0] += 128; q[1] += 128; asm volatile("" : "+v"(q[0]), "+v"(q[1])); } while (0)
; #define LDA(dst, b, h) _Pragma("unroll") for (int m = 0; m < 4; ++m) _Pragma("unroll") for (int k = 0; k < 2; ++k) \
;     dst[m][k] = *(const bf16x8*)((const unsigned char*)SA(b, h) + lds_byte1(wr * 64 + m * 16 + fr, k * 32 + fq * 8))
; #define LDB(dst, b, h) _Pragma("unroll") for (int n = 0; n < 2; ++n) _Pragma("unroll") for (int k = 0; k < 2; ++k) \
;     dst[n][k] = *(const bf16x8*)((const unsigned char*)SB(b, h) + lds_byte1(wc * 32 + n * 16 + fr, k * 32 + fq * 8))
; #define MMA(ai, bj, At_, Bt_) do { __builtin_amdgcn_s_setprio(1); \
;     _Pragma("unroll") for (int m = 0; m < 4; ++m) _Pragma("unroll") for (int n = 0; n < 2; ++n) _Pragma("unroll") for (int k = 0; k < 2; ++k) \
;       acc[ai][bj][m][n] = mfma16(At_[m][k], Bt_[n][k], acc[ai][bj][m][n]); \
;     __builtin_amdgcn_s_setprio(0); } while (0)
; #define WAIT_V(n) asm volatile("s_waitcnt vmcnt(" #n ")" ::: "memory")
; #define WAIT_L(n) asm volatile("s_waitcnt lgkmcnt(" #n ")" ::: "memory")
; #define BAR __builtin_amdgcn_s_barrier()
; DEV void gemm_tile(const u16* __restrict__ A, const u16* __restrict__ Bt, u16* __restrict__ C, int N, int K,
;                    int brow, int bcol, unsigned char* smem, int epi, const GateEpi& ge) {
;     ...
;   { LDB(B0, 0, 0); LDA(At, 0, 0); STAGE(SA(1, 1), qA1);
;     BAR; WAIT_L(0); MMA(0, 0, At, B0); BAR;
;     LDB(B1, 0, 1); BAR; WAIT_L(0); MMA(0, 1, At, B1); BAR;
;     LDA(At, 0, 1); WAIT_V(4); BAR; WAIT_L(0); MMA(1, 0, At, B0); MMA(1, 1, At, B1); BAR; }
;   { LDB(B0, 1, 0); LDA(At, 1, 0); WAIT_V(2); BAR; WAIT_L(0); MMA(0, 0, At, B0); BAR;
;     LDB(B1, 1, 1); WAIT_V(0); BAR; WAIT_L(0); MMA(0, 1, At, B1); BAR;
;     LDA(At, 1, 1); BAR; WAIT_L(0); MMA(1, 0, At, B0); MMA(1, 1, At, B1); BAR; }
;   if (wr == 0) BAR;
	ds_read_b128 v[144:147], v149
	ds_read_b128 v[156:159], v149 offset:1024
	ds_read_b128 v[180:183], v149 offset:256
	ds_read_b128 v[184:187], v149 offset:1280
	s_mov_b32 m0, s41
	ds_read_b128 v[140:143], v128 offset:32768
	ds_read_b128 v[188:191], v128 offset:33792
	ds_read_b128 v[192:195], v153 offset:32768
	ds_read_b128 v[196:199], v153 offset:33792
	ds_read_b128 v[200:203], v154 offset:32768
	ds_read_b128 v[204:207], v154 offset:33792
	ds_read_b128 v[208:211], v155 offset:32768
	ds_read_b128 v[212:215], v155 offset:33792
	s_mov_b32 m0, vcc_lo
	v_lshl_add_u64 v[132:133], v[236:237], 0, s[8:9]
	v_lshl_add_u64 v[134:135], v[238:239], 0, s[8:9]
	s_waitcnt lgkmcnt(8)
	s_barrier
	s_waitcnt lgkmcnt(0)
	s_setprio 1
	s_waitcnt lgkmcnt(0)
	v_mfma_f32_16x16x32_bf16 v[124:127], v[144:147], v[140:143], v[124:127]
	v_mfma_f32_16x16x32_bf16 v[120:123], v[180:183], v[140:143], v[120:123]
	v_mfma_f32_16x16x32_bf16 v[116:119], v[144:147], v[192:195], v[116:119]
	v_mfma_f32_16x16x32_bf16 v[112:115], v[180:183], v[192:195], v[112:115]
	v_mfma_f32_16x16x32_bf16 v[108:111], v[144:147], v[200:203], v[108:111]
	v_mfma_f32_16x16x32_bf16 v[104:107], v[180:183], v[200:203], v[104:107]
	v_mfma_f32_16x16x32_bf16 v[100:103], v[144:147], v[208:211], v[100:103]
	v_mfma_f32_16x16x32_bf16 v[96:99], v[180:183], v[208:211], v[96:99]
	v_mfma_f32_16x16x32_bf16 v[124:127], v[156:159], v[188:191], v[124:127]
	v_mfma_f32_16x16x32_bf16 v[120:123], v[184:187], v[188:191], v[120:123]
	v_mfma_f32_16x16x32_bf16 v[116:119], v[156:159], v[196:199], v[116:119]
	v_mfma_f32_16x16x32_bf16 v[112:115], v[184:187], v[196:199], v[112:115]
	v_mfma_f32_16x16x32_bf16 v[108:111], v[156:159], v[204:207], v[108:111]
	v_mfma_f32_16x16x32_bf16 v[104:107], v[184:187], v[204:207], v[104:107]
	v_mfma_f32_16x16x32_bf16 v[100:103], v[156:159], v[212:215], v[100:103]
	v_mfma_f32_16x16x32_bf16 v[96:99], v[184:187], v[212:215], v[96:99]
	s_setprio 0
	s_barrier
	s_mov_b32 m0, vcc_hi
	ds_read_b128 v[216:219], v148
	ds_read_b128 v[220:223], v148 offset:1024
	ds_read_b128 v[224:227], v148 offset:256
	ds_read_b128 v[228:231], v148 offset:1280
	s_mov_b32 m0, s28
	v_lshl_add_u64 v[136:137], v[240:241], 0, s[8:9]
	v_lshl_add_u64 v[138:139], v[242:243], 0, s[8:9]
	s_barrier
	s_waitcnt lgkmcnt(0)
	s_setprio 1
	s_waitcnt lgkmcnt(0)
	v_mfma_f32_16x16x32_bf16 v[84:87], v[216:219], v[140:143], v[84:87]
	v_mfma_f32_16x16x32_bf16 v[68:71], v[224:227], v[140:143], v[68:71]
	v_mfma_f32_16x16x32_bf16 v[52:55], v[216:219], v[192:195], v[52:55]
	v_mfma_f32_16x16x32_bf16 v[48:51], v[224:227], v[192:195], v[48:51]
	v_mfma_f32_16x16x32_bf16 v[44:47], v[216:219], v[200:203], v[44:47]
	v_mfma_f32_16x16x32_bf16 v[40:43], v[224:227], v[200:203], v[40:43]
	v_mfma_f32_16x16x32_bf16 v[36:39], v[216:219], v[208:211], v[36:39]
	v_mfma_f32_16x16x32_bf16 v[32:35], v[224:227], v[208:211], v[32:35]
	v_mfma_f32_16x16x32_bf16 v[84:87], v[220:223], v[188:191], v[84:87]
	v_mfma_f32_16x16x32_bf16 v[68:71], v[228:231], v[188:191], v[68:71]
	v_mfma_f32_16x16x32_bf16 v[52:55], v[220:223], v[196:199], v[52:55]
	v_mfma_f32_16x16x32_bf16 v[48:51], v[228:231], v[196:199], v[48:51]
	v_mfma_f32_16x16x32_bf16 v[44:47], v[220:223], v[204:207], v[44:47]
	v_mfma_f32_16x16x32_bf16 v[40:43], v[228:231], v[204:207], v[40:43]
	v_mfma_f32_16x16x32_bf16 v[36:39], v[220:223], v[212:215], v[36:39]
	v_mfma_f32_16x16x32_bf16 v[32:35], v[228:231], v[212:215], v[32:35]
	s_setprio 0
	s_mov_b32 m0, s94
	s_barrier
	ds_read_b128 v[188:191], v128 offset:49152
	ds_read_b128 v[192:195], v128 offset:50176
	ds_read_b128 v[196:199], v153 offset:49152
	ds_read_b128 v[200:203], v153 offset:50176
	ds_read_b128 v[204:207], v154 offset:49152
	ds_read_b128 v[208:211], v154 offset:50176
	ds_read_b128 v[212:215], v155 offset:49152
	ds_read_b128 v[232:235], v155 offset:50176
	s_mov_b32 m0, s95
	v_lshl_add_u64 v[140:141], v[244:245], 0, s[8:9]
	v_lshl_add_u64 v[142:143], v[246:247], 0, s[8:9]
	s_barrier
	s_waitcnt lgkmcnt(0)
	s_setprio 1
	s_waitcnt lgkmcnt(0)
	v_mfma_f32_16x16x32_bf16 v[28:31], v[144:147], v[188:191], v[28:31]
	v_mfma_f32_16x16x32_bf16 v[24:27], v[180:183], v[188:191], v[24:27]
	v_mfma_f32_16x16x32_bf16 v[20:23], v[144:147], v[196:199], v[20:23]
	v_mfma_f32_16x16x32_bf16 v[16:19], v[180:183], v[196:199], v[16:19]
	v_mfma_f32_16x16x32_bf16 v[12:15], v[144:147], v[204:207], v[12:15]
	v_mfma_f32_16x16x32_bf16 v[8:11], v[180:183], v[204:207], v[8:11]
	v_mfma_f32_16x16x32_bf16 v[4:7], v[144:147], v[212:215], v[4:7]
	v_mfma_f32_16x16x32_bf16 v[0:3], v[180:183], v[212:215], v[0:3]
	v_mfma_f32_16x16x32_bf16 v[28:31], v[156:159], v[192:195], v[28:31]
	v_mfma_f32_16x16x32_bf16 v[24:27], v[184:187], v[192:195], v[24:27]
	v_mfma_f32_16x16x32_bf16 v[20:23], v[156:159], v[200:203], v[20:23]
	v_mfma_f32_16x16x32_bf16 v[16:19], v[184:187], v[200:203], v[16:19]
	v_mfma_f32_16x16x32_bf16 v[12:15], v[156:159], v[208:211], v[12:15]
	v_mfma_f32_16x16x32_bf16 v[8:11], v[184:187], v[208:211], v[8:11]
	v_mfma_f32_16x16x32_bf16 v[4:7], v[156:159], v[232:235], v[4:7]
	v_mfma_f32_16x16x32_bf16 v[0:3], v[184:187], v[232:235], v[0:3]
	s_setprio 0
	s_barrier
	s_mov_b32 m0, s62
	v_lshl_add_u64 v[144:145], v[248:249], 0, s[8:9]
	s_mov_b32 m0, s63
	v_lshl_add_u64 v[146:147], v[250:251], 0, s[8:9]
	s_waitcnt vmcnt(0)
	s_barrier
	s_setprio 1
	v_mfma_f32_16x16x32_bf16 v[56:59], v[216:219], v[188:191], v[56:59]
	v_mfma_f32_16x16x32_bf16 v[60:63], v[224:227], v[188:191], v[60:63]
	v_mfma_f32_16x16x32_bf16 v[64:67], v[216:219], v[196:199], v[64:67]
	v_mfma_f32_16x16x32_bf16 v[72:75], v[224:227], v[196:199], v[72:75]
	v_mfma_f32_16x16x32_bf16 v[76:79], v[216:219], v[204:207], v[76:79]
	v_mfma_f32_16x16x32_bf16 v[80:83], v[224:227], v[204:207], v[80:83]
	v_mfma_f32_16x16x32_bf16 v[88:91], v[216:219], v[212:215], v[88:91]
	v_mfma_f32_16x16x32_bf16 v[92:95], v[224:227], v[212:215], v[92:95]
	v_mfma_f32_16x16x32_bf16 v[56:59], v[220:223], v[192:195], v[56:59]
	v_mfma_f32_16x16x32_bf16 v[60:63], v[228:231], v[192:195], v[60:63]
	v_mfma_f32_16x16x32_bf16 v[64:67], v[220:223], v[200:203], v[64:67]
	v_mfma_f32_16x16x32_bf16 v[72:75], v[228:231], v[200:203], v[72:75]
	v_mfma_f32_16x16x32_bf16 v[76:79], v[220:223], v[208:211], v[76:79]
	v_mfma_f32_16x16x32_bf16 v[80:83], v[228:231], v[208:211], v[80:83]
	v_mfma_f32_16x16x32_bf16 v[88:91], v[220:223], v[232:235], v[88:91]
	v_mfma_f32_16x16x32_bf16 v[92:95], v[228:231], v[232:235], v[92:95]
	s_setprio 0
	s_barrier
	s_mov_b32 s63, 0
	s_branch .Lg_unstag

; #define STAGE(P, q) do { GLDS16(q[0], (unsigned char*)(P) + wid * 1024); GLDS16(q[1], (unsigned char*)(P) + wid * 1024 + 8192); \
;     q[0] += 128; q[1] += 128; asm volatile("" : "+v"(q[0]), "+v"(q[1])); } while (0)
; #define LDA(dst, b, h) _Pragma("unroll") for (int m = 0; m < 4; ++m) _Pragma("unroll") for (int k = 0; k < 2; ++k) \
;     dst[m][k] = *(const bf16x8*)((const unsigned char*)SA(b, h) + lds_byte1(wr * 64 + m * 16 + fr, k * 32 + fq * 8))
; #define LDB(dst, b, h) _Pragma("unroll") for (int n = 0; n < 2; ++n) _Pragma("unroll") for (int k = 0; k < 2; ++k) \
;     dst[n][k] = *(const bf16x8*)((const unsigned char*)SB(b, h) + lds_byte1(wc * 32 + n * 16 + fr, k * 32 + fq * 8))
; #define MMA(ai, bj, At_, Bt_) do { __builtin_amdgcn_s_setprio(1); \
;     _Pragma("unroll") for (int m = 0; m < 4; ++m) _Pragma("unroll") for (int n = 0; n < 2; ++n) _Pragma("unroll") for (int k = 0; k < 2; ++k) \
;       acc[ai][bj][m][n] = mfma16(At_[m][k], Bt_[n][k], acc[ai][bj][m][n]); \
;     __builtin_amdgcn_s_setprio(0); } while (0)
; #define WAIT_V(n) asm volatile("s_waitcnt vmcnt(" #n ")" ::: "memory")
; #define WAIT_L(n) asm volatile("s_waitcnt lgkmcnt(" #n ")" ::: "memory")
; #define BAR __builtin_amdgcn_s_barrier()
; DEV void gemm_tile(const u16* __restrict__ A, const u16* __restrict__ Bt, u16* __restrict__ C, int N, int K,
;                    int brow, int bcol, unsigned char* smem, int epi, const GateEpi& ge) {
;     ...
;   { LDB(B0, 0, 0); LDA(At, 0, 0); STAGE(SA(1, 1), qA1);
;     BAR; WAIT_L(0); MMA(0, 0, At, B0); BAR;
;     LDB(B1, 0, 1); BAR; WAIT_L(0); MMA(0, 1, At, B1); BAR;
;     LDA(At, 0, 1); WAIT_V(4); BAR; WAIT_L(0); MMA(1, 0, At, B0); MMA(1, 1, At, B1); BAR; }
;   { LDB(B0, 1, 0); LDA(At, 1, 0); WAIT_V(2); BAR; WAIT_L(0); MMA(0, 0, At, B0); BAR;
;     LDB(B1, 1, 1); WAIT_V(0); BAR; WAIT_L(0); MMA(0, 1, At, B1); BAR;
;     LDA(At, 1, 1); BAR; WAIT_L(0); MMA(1, 0, At, B0); MMA(1, 1, At, B1); BAR; }
;     ...
;     const int pm = brow >> 8, pn = bcol >> 8;
;     float w0[2], w1[2], w2[2], bs[2];
; #pragma unroll
;     for (int n = 0; n < 2; ++n) {
;       const int cg = pn * 128 + wc * 32 + n * 16 + fr2;
;       w0[n] = ge.cw[cg]; w1[n] = ge.cw[DFF + cg]; w2[n] = ge.cw[2 * DFF + cg]; bs[n] = ge.cb[cg];
;     }
.Lg_normdone:
	v_writelane_b32 v252, s0, 42
	v_writelane_b32 v252, s58, 43
	s_lshl_b32 s59, s0, 8
	s_and_b32 s59, s59, 0x700
	s_lshl_b32 s58, s58, 11
	s_or_b32 s59, s58, s59
	s_lshl_b32 s53, s0, 5
	s_and_b32 s53, s53, 0xffffff00
	s_sub_i32 s59, s59, s49
	s_add_i32 s59, s59, -1
	s_sub_i32 s53, s53, s92
	s_add_i32 s53, s53, -1
	s_lshl_b32 s0, s18, 1
	s_mul_hi_i32 s55, s59, s0
	s_mul_i32 s54, s59, s0
	v_lshl_add_u64 v[140:141], v[140:141], 0, s[54:55]
	v_lshl_add_u64 v[142:143], v[142:143], 0, s[54:55]
	v_lshl_add_u64 v[236:237], v[236:237], 0, s[54:55]
	v_lshl_add_u64 v[238:239], v[238:239], 0, s[54:55]
	s_mul_hi_i32 s55, s53, s0
	s_mul_i32 s54, s53, s0
	v_lshl_add_u64 v[136:137], v[136:137], 0, s[54:55]
	v_lshl_add_u64 v[138:139], v[138:139], 0, s[54:55]
	v_lshl_add_u64 v[144:145], v[144:145], 0, s[54:55]
	v_lshl_add_u64 v[146:147], v[146:147], 0, s[54:55]
	s_andn2_b64 s[54:55], exec, s[2:3]
	s_cmp_lg_u64 s[54:55], 0
	s_cbranch_scc1 .Lwdma_skip_last
	v_readlane_b32 s54, v252, 38
	v_readlane_b32 s55, v252, 39
	v_readlane_b32 s58, v252, 40
	v_readlane_b32 s59, v252, 41
	s_lshl_b32 s0, s47, 6
	s_and_b32 s0, s0, 0xfffffe00
	s_lshl_b32 s53, s50, 7
	s_add_i32 s0, s0, s53
	v_mbcnt_lo_u32_b32 v224, -1, 0
	v_mbcnt_hi_u32_b32 v224, -1, v224
	v_and_b32_e32 v230, 7, v224
	v_lshlrev_b32_e32 v230, 4, v230
	v_add_u32_e32 v230, s0, v230
	v_bfe_u32 v226, v224, 3, 2
	v_mul_u32_u24_e32 v228, 0x5800, v226
	v_add_u32_e32 v228, v228, v230
	v_mov_b32_e32 v229, 0
	v_mov_b32_e32 v231, 0
	v_lshl_add_u64 v[232:233], s[54:55], 0, v[228:229]
	v_lshl_add_u64 v[234:235], s[58:59], 0, v[230:231]
	v_cmp_eq_u32_e64 s[54:55], 3, v226
	s_add_i32 s0, s1, 0x21000
	s_mov_b32 m0, s0
	v_cndmask_b32_e64 v232, v232, v234, s[54:55]
	v_cndmask_b32_e64 v233, v233, v235, s[54:55]
	s_nop 1
	global_load_lds_dwordx4 v[232:233], off
.Lwdma_skip_last:
	s_waitcnt lgkmcnt(8)
	s_barrier
	s_waitcnt lgkmcnt(0)
	s_setprio 1
	s_waitcnt lgkmcnt(0)
	v_mfma_f32_16x16x32_bf16 v[124:127], v[156:159], v[192:195], v[124:127]
	v_mfma_f32_16x16x32_bf16 v[120:123], v[184:187], v[192:195], v[120:123]
	v_mfma_f32_16x16x32_bf16 v[116:119], v[156:159], v[200:203], v[116:119]
	v_mfma_f32_16x16x32_bf16 v[112:115], v[184:187], v[200:203], v[112:115]
	v_mfma_f32_16x16x32_bf16 v[108:111], v[156:159], v[208:211], v[108:111]
	v_mfma_f32_16x16x32_bf16 v[104:107], v[184:187], v[208:211], v[104:107]
	v_mfma_f32_16x16x32_bf16 v[100:103], v[156:159], v[216:219], v[100:103]
	v_mfma_f32_16x16x32_bf16 v[96:99], v[184:187], v[216:219], v[96:99]
	v_mfma_f32_16x16x32_bf16 v[124:127], v[180:183], v[196:199], v[124:127]
	v_mfma_f32_16x16x32_bf16 v[120:123], v[188:191], v[196:199], v[120:123]
	v_mfma_f32_16x16x32_bf16 v[116:119], v[180:183], v[204:207], v[116:119]
	v_mfma_f32_16x16x32_bf16 v[112:115], v[188:191], v[204:207], v[112:115]
	v_mfma_f32_16x16x32_bf16 v[108:111], v[180:183], v[212:215], v[108:111]
	v_mfma_f32_16x16x32_bf16 v[104:107], v[188:191], v[212:215], v[104:107]
	v_mfma_f32_16x16x32_bf16 v[100:103], v[180:183], v[220:223], v[100:103]
	v_mfma_f32_16x16x32_bf16 v[96:99], v[188:191], v[220:223], v[96:99]
	s_setprio 0
	s_barrier
	s_mov_b32 m0, s4
	ds_read_b128 v[132:135], v150
	ds_read_b128 v[224:227], v150 offset:1024
	ds_read_b128 v[228:231], v150 offset:256
	ds_read_b128 v[232:235], v150 offset:1280
	global_load_lds_dwordx4 v[136:137], off
	s_mov_b32 m0, s5
	v_lshl_add_u64 v[240:241], v[136:137], 0, s[8:9]
	global_load_lds_dwordx4 v[138:139], off
	v_lshl_add_u64 v[242:243], v[138:139], 0, s[8:9]
	s_barrier
	s_waitcnt lgkmcnt(0)
	s_setprio 1
	s_waitcnt lgkmcnt(0)
	v_mfma_f32_16x16x32_bf16 v[84:87], v[132:135], v[192:195], v[84:87]
	v_mfma_f32_16x16x32_bf16 v[68:71], v[228:231], v[192:195], v[68:71]
	v_mfma_f32_16x16x32_bf16 v[52:55], v[132:135], v[200:203], v[52:55]
	v_mfma_f32_16x16x32_bf16 v[48:51], v[228:231], v[200:203], v[48:51]
	v_mfma_f32_16x16x32_bf16 v[44:47], v[132:135], v[208:211], v[44:47]
	v_mfma_f32_16x16x32_bf16 v[40:43], v[228:231], v[208:211], v[40:43]
	v_mfma_f32_16x16x32_bf16 v[36:39], v[132:135], v[216:219], v[36:39]
	v_mfma_f32_16x16x32_bf16 v[32:35], v[228:231], v[216:219], v[32:35]
	v_mfma_f32_16x16x32_bf16 v[84:87], v[224:227], v[196:199], v[84:87]
	v_mfma_f32_16x16x32_bf16 v[68:71], v[232:235], v[196:199], v[68:71]
	v_mfma_f32_16x16x32_bf16 v[52:55], v[224:227], v[204:207], v[52:55]
	v_mfma_f32_16x16x32_bf16 v[48:51], v[232:235], v[204:207], v[48:51]
	v_mfma_f32_16x16x32_bf16 v[44:47], v[224:227], v[212:215], v[44:47]
	v_mfma_f32_16x16x32_bf16 v[40:43], v[232:235], v[212:215], v[40:43]
	v_mfma_f32_16x16x32_bf16 v[36:39], v[224:227], v[220:223], v[36:39]
	v_mfma_f32_16x16x32_bf16 v[32:35], v[232:235], v[220:223], v[32:35]
	s_setprio 0
	s_mov_b32 m0, s1
	s_barrier
	ds_read_b128 v[136:139], v128 offset:16384
	ds_read_b128 v[192:195], v128 offset:17408
	ds_read_b128 v[196:199], v153 offset:16384
	ds_read_b128 v[200:203], v153 offset:17408
	ds_read_b128 v[204:207], v154 offset:16384
	ds_read_b128 v[208:211], v154 offset:17408
	ds_read_b128 v[212:215], v155 offset:16384
	ds_read_b128 v[216:219], v155 offset:17408
	global_load_lds_dwordx4 v[140:141], off
	s_mov_b32 m0, s6
	v_lshl_add_u64 v[244:245], v[140:141], 0, s[8:9]
	global_load_lds_dwordx4 v[142:143], off
	v_lshl_add_u64 v[246:247], v[142:143], 0, s[8:9]
	s_barrier
; #define STAGE(P, q) do { GLDS16(q[0], (unsigned char*)(P) + wid * 1024); GLDS16(q[1], (unsigned char*)(P) + wid * 1024 + 8192); \
;     q[0] += 128; q[1] += 128; asm volatile("" : "+v"(q[0]), "+v"(q[1])); } while (0)
; #define LDA(dst, b, h) _Pragma("unroll") for (int m = 0; m < 4; ++m) _Pragma("unroll") for (int k = 0; k < 2; ++k) \
;     dst[m][k] = *(const bf16x8*)((const unsigned char*)SA(b, h) + lds_byte1(wr * 64 + m * 16 + fr, k * 32 + fq * 8))
; #define LDB(dst, b, h) _Pragma("unroll") for (int n = 0; n < 2; ++n) _Pragma("unroll") for (int k = 0; k < 2; ++k) \
;     dst[n][k] = *(const bf16x8*)((const unsigned char*)SB(b, h) + lds_byte1(wc * 32 + n * 16 + fr, k * 32 + fq * 8))
; #define MMA(ai, bj, At_, Bt_) do { __builtin_amdgcn_s_setprio(1); \
;     _Pragma("unroll") for (int m = 0; m < 4; ++m) _Pragma("unroll") for (int n = 0; n < 2; ++n) _Pragma("unroll") for (int k = 0; k < 2; ++k) \
;       acc[ai][bj][m][n] = mfma16(At_[m][k], Bt_[n][k], acc[ai][bj][m][n]); \
;     __builtin_amdgcn_s_setprio(0); } while (0)
; #define WAIT_V(n) asm volatile("s_waitcnt vmcnt(" #n ")" ::: "memory")
; #define WAIT_L(n) asm volatile("s_waitcnt lgkmcnt(" #n ")" ::: "memory")
; #define BAR __builtin_amdgcn_s_barrier()
; DEV void gemm_tile(const u16* __restrict__ A, const u16* __restrict__ Bt, u16* __restrict__ C, int N, int K,
;                    int brow, int bcol, unsigned char* smem, int epi, const GateEpi& ge) {
;     ...
;   { LDB(B0, 0, 0); LDA(At, 0, 0); STAGE(SA(1, 1), qA1);
;     BAR; WAIT_L(0); MMA(0, 0, At, B0); BAR;
;     LDB(B1, 0, 1); BAR; WAIT_L(0); MMA(0, 1, At, B1); BAR;
;     LDA(At, 0, 1); WAIT_V(4); BAR; WAIT_L(0); MMA(1, 0, At, B0); MMA(1, 1, At, B1); BAR; }
;   { LDB(B0, 1, 0); LDA(At, 1, 0); WAIT_V(2); BAR; WAIT_L(0); MMA(0, 0, At, B0); BAR;
;     LDB(B1, 1, 1); WAIT_V(0); BAR; WAIT_L(0); MMA(0, 1, At, B1); BAR;
;     LDA(At, 1, 1); BAR; WAIT_L(0); MMA(1, 0, At, B0); MMA(1, 1, At, B1); BAR; }
	s_waitcnt lgkmcnt(0)
	s_setprio 1
	s_waitcnt lgkmcnt(0)
	v_mfma_f32_16x16x32_bf16 v[28:31], v[156:159], v[136:139], v[28:31]
	v_mfma_f32_16x16x32_bf16 v[24:27], v[184:187], v[136:139], v[24:27]
	v_mfma_f32_16x16x32_bf16 v[20:23], v[156:159], v[196:199], v[20:23]
	v_mfma_f32_16x16x32_bf16 v[16:19], v[184:187], v[196:199], v[16:19]
	v_mfma_f32_16x16x32_bf16 v[12:15], v[156:159], v[204:207], v[12:15]
	v_mfma_f32_16x16x32_bf16 v[8:11], v[184:187], v[204:207], v[8:11]
	v_mfma_f32_16x16x32_bf16 v[4:7], v[156:159], v[212:215], v[4:7]
	v_mfma_f32_16x16x32_bf16 v[0:3], v[184:187], v[212:215], v[0:3]
	v_mfma_f32_16x16x32_bf16 v[28:31], v[180:183], v[192:195], v[28:31]
	v_mfma_f32_16x16x32_bf16 v[24:27], v[188:191], v[192:195], v[24:27]
	v_mfma_f32_16x16x32_bf16 v[20:23], v[180:183], v[200:203], v[20:23]
	v_mfma_f32_16x16x32_bf16 v[16:19], v[188:191], v[200:203], v[16:19]
	v_mfma_f32_16x16x32_bf16 v[12:15], v[180:183], v[208:211], v[12:15]
	v_mfma_f32_16x16x32_bf16 v[8:11], v[188:191], v[208:211], v[8:11]
	v_mfma_f32_16x16x32_bf16 v[4:7], v[180:183], v[216:219], v[4:7]
	v_mfma_f32_16x16x32_bf16 v[0:3], v[188:191], v[216:219], v[0:3]
	s_setprio 0
	s_barrier
	s_mov_b32 m0, s7
	v_lshl_add_u64 v[248:249], v[144:145], 0, s[8:9]
	global_load_lds_dwordx4 v[144:145], off
	s_mov_b32 m0, s35
	v_lshl_add_u64 v[250:251], v[146:147], 0, s[8:9]
	global_load_lds_dwordx4 v[146:147], off
	s_waitcnt vmcnt(6)
	s_barrier
	s_setprio 1
	v_mfma_f32_16x16x32_bf16 v[56:59], v[132:135], v[136:139], v[56:59]
	v_mfma_f32_16x16x32_bf16 v[60:63], v[228:231], v[136:139], v[60:63]
	v_mfma_f32_16x16x32_bf16 v[64:67], v[132:135], v[196:199], v[64:67]
	v_mfma_f32_16x16x32_bf16 v[72:75], v[228:231], v[196:199], v[72:75]
	v_mfma_f32_16x16x32_bf16 v[76:79], v[132:135], v[204:207], v[76:79]
	v_mfma_f32_16x16x32_bf16 v[80:83], v[228:231], v[204:207], v[80:83]
	v_mfma_f32_16x16x32_bf16 v[88:91], v[132:135], v[212:215], v[88:91]
	v_mfma_f32_16x16x32_bf16 v[92:95], v[228:231], v[212:215], v[92:95]
	v_mfma_f32_16x16x32_bf16 v[56:59], v[224:227], v[192:195], v[56:59]
	v_mfma_f32_16x16x32_bf16 v[60:63], v[232:235], v[192:195], v[60:63]
	v_mfma_f32_16x16x32_bf16 v[64:67], v[224:227], v[200:203], v[64:67]
	v_mfma_f32_16x16x32_bf16 v[72:75], v[232:235], v[200:203], v[72:75]
	v_mfma_f32_16x16x32_bf16 v[76:79], v[224:227], v[208:211], v[76:79]
	v_mfma_f32_16x16x32_bf16 v[80:83], v[232:235], v[208:211], v[80:83]
	v_mfma_f32_16x16x32_bf16 v[88:91], v[224:227], v[216:219], v[88:91]
	v_mfma_f32_16x16x32_bf16 v[92:95], v[232:235], v[216:219], v[92:95]
	s_setprio 0
	s_barrier
	ds_read_b128 v[144:147], v149
	ds_read_b128 v[156:159], v149 offset:1024
	ds_read_b128 v[180:183], v149 offset:256
	ds_read_b128 v[184:187], v149 offset:1280
	s_mov_b32 m0, s41
	ds_read_b128 v[140:143], v128 offset:32768
	ds_read_b128 v[188:191], v128 offset:33792
	ds_read_b128 v[192:195], v153 offset:32768
	ds_read_b128 v[196:199], v153 offset:33792
	ds_read_b128 v[200:203], v154 offset:32768
	ds_read_b128 v[204:207], v154 offset:33792
	ds_read_b128 v[208:211], v155 offset:32768
	ds_read_b128 v[212:215], v155 offset:33792
	global_load_lds_dwordx4 v[236:237], off
	s_mov_b32 m0, vcc_lo
	v_lshl_add_u64 v[132:133], v[236:237], 0, s[8:9]
	global_load_lds_dwordx4 v[238:239], off
	v_lshl_add_u64 v[134:135], v[238:239], 0, s[8:9]
	s_waitcnt lgkmcnt(8)
	s_barrier
	s_waitcnt lgkmcnt(0)
	s_setprio 1
	s_waitcnt lgkmcnt(0)
	v_mfma_f32_16x16x32_bf16 v[124:127], v[144:147], v[140:143], v[124:127]
	v_mfma_f32_16x16x32_bf16 v[120:123], v[180:183], v[140:143], v[120:123]
	v_mfma_f32_16x16x32_bf16 v[116:119], v[144:147], v[192:195], v[116:119]
	v_mfma_f32_16x16x32_bf16 v[112:115], v[180:183], v[192:195], v[112:115]
	v_mfma_f32_16x16x32_bf16 v[108:111], v[144:147], v[200:203], v[108:111]
	v_mfma_f32_16x16x32_bf16 v[104:107], v[180:183], v[200:203], v[104:107]
	v_mfma_f32_16x16x32_bf16 v[100:103], v[144:147], v[208:211], v[100:103]
	v_mfma_f32_16x16x32_bf16 v[96:99], v[180:183], v[208:211], v[96:99]
	v_mfma_f32_16x16x32_bf16 v[124:127], v[156:159], v[188:191], v[124:127]
	v_mfma_f32_16x16x32_bf16 v[120:123], v[184:187], v[188:191], v[120:123]
	v_mfma_f32_16x16x32_bf16 v[116:119], v[156:159], v[196:199], v[116:119]
	v_mfma_f32_16x16x32_bf16 v[112:115], v[184:187], v[196:199], v[112:115]
	v_mfma_f32_16x16x32_bf16 v[108:111], v[156:159], v[204:207], v[108:111]
	v_mfma_f32_16x16x32_bf16 v[104:107], v[184:187], v[204:207], v[104:107]
	v_mfma_f32_16x16x32_bf16 v[100:103], v[156:159], v[212:215], v[100:103]
	v_mfma_f32_16x16x32_bf16 v[96:99], v[184:187], v[212:215], v[96:99]
	s_setprio 0
	s_barrier
; #define STAGE(P, q) do { GLDS16(q[0], (unsigned char*)(P) + wid * 1024); GLDS16(q[1], (unsigned char*)(P) + wid * 1024 + 8192); \
;     q[0] += 128; q[1] += 128; asm volatile("" : "+v"(q[0]), "+v"(q[1])); } while (0)
; #define LDA(dst, b, h) _Pragma("unroll") for (int m = 0; m < 4; ++m) _Pragma("unroll") for (int k = 0; k < 2; ++k) \
;     dst[m][k] = *(const bf16x8*)((const unsigned char*)SA(b, h) + lds_byte1(wr * 64 + m * 16 + fr, k * 32 + fq * 8))
; #define LDB(dst, b, h) _Pragma("unroll") for (int n = 0; n < 2; ++n) _Pragma("unroll") for (int k = 0; k < 2; ++k) \
;     dst[n][k] = *(const bf16x8*)((const unsigned char*)SB(b, h) + lds_byte1(wc * 32 + n * 16 + fr, k * 32 + fq * 8))
; #define MMA(ai, bj, At_, Bt_) do { __builtin_amdgcn_s_setprio(1); \
;     _Pragma("unroll") for (int m = 0; m < 4; ++m) _Pragma("unroll") for (int n = 0; n < 2; ++n) _Pragma("unroll") for (int k = 0; k < 2; ++k) \
;       acc[ai][bj][m][n] = mfma16(At_[m][k], Bt_[n][k], acc[ai][bj][m][n]); \
;     __builtin_amdgcn_s_setprio(0); } while (0)
; #define WAIT_V(n) asm volatile("s_waitcnt vmcnt(" #n ")" ::: "memory")
; #define WAIT_L(n) asm volatile("s_waitcnt lgkmcnt(" #n ")" ::: "memory")
; #define BAR __builtin_amdgcn_s_barrier()
; DEV void gemm_tile(const u16* __restrict__ A, const u16* __restrict__ Bt, u16* __restrict__ C, int N, int K,
;                    int brow, int bcol, unsigned char* smem, int epi, const GateEpi& ge) {
;     ...
;   { LDB(B0, 0, 0); LDA(At, 0, 0); STAGE(SA(1, 1), qA1);
;     BAR; WAIT_L(0); MMA(0, 0, At, B0); BAR;
;     LDB(B1, 0, 1); BAR; WAIT_L(0); MMA(0, 1, At, B1); BAR;
;     LDA(At, 0, 1); WAIT_V(4); BAR; WAIT_L(0); MMA(1, 0, At, B0); MMA(1, 1, At, B1); BAR; }
;   { LDB(B0, 1, 0); LDA(At, 1, 0); WAIT_V(2); BAR; WAIT_L(0); MMA(0, 0, At, B0); BAR;
;     LDB(B1, 1, 1); WAIT_V(0); BAR; WAIT_L(0); MMA(0, 1, At, B1); BAR;
;     LDA(At, 1, 1); BAR; WAIT_L(0); MMA(1, 0, At, B0); MMA(1, 1, At, B1); BAR; }
;   if (wr == 0) BAR;
;   const int tid2 = tidx(), lane2 = tid2 & 63, fr2 = lane2 & 15, fq2 = lane2 >> 4;
;   if (epi) {
	s_mov_b32 m0, vcc_hi
	ds_read_b128 v[216:219], v148
	ds_read_b128 v[220:223], v148 offset:1024
	ds_read_b128 v[224:227], v148 offset:256
	ds_read_b128 v[228:231], v148 offset:1280
	global_load_lds_dwordx4 v[240:241], off
	s_mov_b32 m0, s28
	v_lshl_add_u64 v[136:137], v[240:241], 0, s[8:9]
	global_load_lds_dwordx4 v[242:243], off
	v_lshl_add_u64 v[138:139], v[242:243], 0, s[8:9]
	s_barrier
	s_waitcnt lgkmcnt(0)
	s_setprio 1
	s_waitcnt lgkmcnt(0)
	v_mfma_f32_16x16x32_bf16 v[84:87], v[216:219], v[140:143], v[84:87]
	v_mfma_f32_16x16x32_bf16 v[68:71], v[224:227], v[140:143], v[68:71]
	v_mfma_f32_16x16x32_bf16 v[52:55], v[216:219], v[192:195], v[52:55]
	v_mfma_f32_16x16x32_bf16 v[48:51], v[224:227], v[192:195], v[48:51]
	v_mfma_f32_16x16x32_bf16 v[44:47], v[216:219], v[200:203], v[44:47]
	v_mfma_f32_16x16x32_bf16 v[40:43], v[224:227], v[200:203], v[40:43]
	v_mfma_f32_16x16x32_bf16 v[36:39], v[216:219], v[208:211], v[36:39]
	v_mfma_f32_16x16x32_bf16 v[32:35], v[224:227], v[208:211], v[32:35]
	v_mfma_f32_16x16x32_bf16 v[84:87], v[220:223], v[188:191], v[84:87]
	v_mfma_f32_16x16x32_bf16 v[68:71], v[228:231], v[188:191], v[68:71]
	v_mfma_f32_16x16x32_bf16 v[52:55], v[220:223], v[196:199], v[52:55]
	v_mfma_f32_16x16x32_bf16 v[48:51], v[228:231], v[196:199], v[48:51]
	v_mfma_f32_16x16x32_bf16 v[44:47], v[220:223], v[204:207], v[44:47]
	v_mfma_f32_16x16x32_bf16 v[40:43], v[228:231], v[204:207], v[40:43]
	v_mfma_f32_16x16x32_bf16 v[36:39], v[220:223], v[212:215], v[36:39]
	v_mfma_f32_16x16x32_bf16 v[32:35], v[228:231], v[212:215], v[32:35]
	s_setprio 0
	s_mov_b32 m0, s94
	s_barrier
	ds_read_b128 v[188:191], v128 offset:49152
	ds_read_b128 v[192:195], v128 offset:50176
	ds_read_b128 v[196:199], v153 offset:49152
	ds_read_b128 v[200:203], v153 offset:50176
	ds_read_b128 v[204:207], v154 offset:49152
	ds_read_b128 v[208:211], v154 offset:50176
	ds_read_b128 v[212:215], v155 offset:49152
	ds_read_b128 v[232:235], v155 offset:50176
	global_load_lds_dwordx4 v[244:245], off
	s_mov_b32 m0, s95
	v_lshl_add_u64 v[140:141], v[244:245], 0, s[8:9]
	global_load_lds_dwordx4 v[246:247], off
	v_lshl_add_u64 v[142:143], v[246:247], 0, s[8:9]
	s_barrier
	s_waitcnt lgkmcnt(0)
	s_setprio 1
	s_waitcnt lgkmcnt(0)
	v_mfma_f32_16x16x32_bf16 v[28:31], v[144:147], v[188:191], v[28:31]
	v_mfma_f32_16x16x32_bf16 v[24:27], v[180:183], v[188:191], v[24:27]
	v_mfma_f32_16x16x32_bf16 v[20:23], v[144:147], v[196:199], v[20:23]
	v_mfma_f32_16x16x32_bf16 v[16:19], v[180:183], v[196:199], v[16:19]
	v_mfma_f32_16x16x32_bf16 v[12:15], v[144:147], v[204:207], v[12:15]
	v_mfma_f32_16x16x32_bf16 v[8:11], v[180:183], v[204:207], v[8:11]
	v_mfma_f32_16x16x32_bf16 v[4:7], v[144:147], v[212:215], v[4:7]
	v_mfma_f32_16x16x32_bf16 v[0:3], v[180:183], v[212:215], v[0:3]
	v_mfma_f32_16x16x32_bf16 v[28:31], v[156:159], v[192:195], v[28:31]
	v_mfma_f32_16x16x32_bf16 v[24:27], v[184:187], v[192:195], v[24:27]
	v_mfma_f32_16x16x32_bf16 v[20:23], v[156:159], v[200:203], v[20:23]
	v_mfma_f32_16x16x32_bf16 v[16:19], v[184:187], v[200:203], v[16:19]
	v_mfma_f32_16x16x32_bf16 v[12:15], v[156:159], v[208:211], v[12:15]
	v_mfma_f32_16x16x32_bf16 v[8:11], v[184:187], v[208:211], v[8:11]
	v_mfma_f32_16x16x32_bf16 v[4:7], v[156:159], v[232:235], v[4:7]
	v_mfma_f32_16x16x32_bf16 v[0:3], v[184:187], v[232:235], v[0:3]
	s_setprio 0
	s_barrier
	s_mov_b32 m0, s62
	v_lshl_add_u64 v[144:145], v[248:249], 0, s[8:9]
	global_load_lds_dwordx4 v[248:249], off
	s_mov_b32 m0, s63
	v_lshl_add_u64 v[146:147], v[250:251], 0, s[8:9]
	global_load_lds_dwordx4 v[250:251], off
	s_waitcnt vmcnt(6)
	s_barrier
	s_setprio 1
	v_mfma_f32_16x16x32_bf16 v[56:59], v[216:219], v[188:191], v[56:59]
	v_mfma_f32_16x16x32_bf16 v[60:63], v[224:227], v[188:191], v[60:63]
	v_mfma_f32_16x16x32_bf16 v[64:67], v[216:219], v[196:199], v[64:67]
	v_mfma_f32_16x16x32_bf16 v[72:75], v[224:227], v[196:199], v[72:75]
	v_mfma_f32_16x16x32_bf16 v[76:79], v[216:219], v[204:207], v[76:79]
	v_mfma_f32_16x16x32_bf16 v[80:83], v[224:227], v[204:207], v[80:83]
	v_mfma_f32_16x16x32_bf16 v[88:91], v[216:219], v[212:215], v[88:91]
	v_mfma_f32_16x16x32_bf16 v[92:95], v[224:227], v[212:215], v[92:95]
	v_mfma_f32_16x16x32_bf16 v[56:59], v[220:223], v[192:195], v[56:59]
	v_mfma_f32_16x16x32_bf16 v[60:63], v[228:231], v[192:195], v[60:63]
	v_mfma_f32_16x16x32_bf16 v[64:67], v[220:223], v[200:203], v[64:67]
	v_mfma_f32_16x16x32_bf16 v[72:75], v[228:231], v[200:203], v[72:75]
	v_mfma_f32_16x16x32_bf16 v[76:79], v[220:223], v[208:211], v[76:79]
	v_mfma_f32_16x16x32_bf16 v[80:83], v[228:231], v[208:211], v[80:83]
	v_mfma_f32_16x16x32_bf16 v[88:91], v[220:223], v[232:235], v[88:91]
	v_mfma_f32_16x16x32_bf16 v[92:95], v[228:231], v[232:235], v[92:95]
	s_setprio 0
	s_barrier
	s_mov_b32 s63, 1
.Lg_unstag:
	s_andn2_b64 vcc, exec, s[2:3]
	s_cbranch_vccz .Lg_do_unstag
	s_cmp_eq_u32 s63, 1
	s_cbranch_scc1 .Lg_epi

; DEV void gemm_tile(const u16* __restrict__ A, const u16* __restrict__ Bt, u16* __restrict__ C, int N, int K,
;                    int brow, int bcol, unsigned char* smem, int epi, const GateEpi& ge) {
;     ...
;   if (epi) {
;     u16* sAt = (u16*)smem;
;     constexpr int AS = 132;
;     __syncthreads();
; #pragma unroll
;     for (int ai = 0; ai < 2; ++ai)
; #pragma unroll
;       for (int m = 0; m < 4; ++m)
; #pragma unroll
;         for (int n = 0; n < 2; ++n)
; #pragma unroll
;           for (int j = 0; j < 4; ++j)
;             sAt[(ai * 128 + wr * 64 + m * 16 + fq2 * 4 + j) * AS + wc * 32 + n * 16 + fr2] = f2bf(acc[ai][0][m][n][j]);
;     __syncthreads();
;     __builtin_amdgcn_sched_barrier(0);
;     const int pm = brow >> 8, pn = bcol >> 8;
;     float w0[2], w1[2], w2[2], bs[2];
; #pragma unroll
;     for (int n = 0; n < 2; ++n) {
;       const int cg = pn * 128 + wc * 32 + n * 16 + fr2;
;       w0[n] = ge.cw[cg]; w1[n] = ge.cw[DFF + cg]; w2[n] = ge.cw[2 * DFF + cg]; bs[n] = ge.cb[cg];
;     }
.Lg_gate:
	s_add_i32 s62, s1, 0x21000
	v_lshlrev_b32_e32 v154, 5, v181
	v_add_u32_e32 v154, s62, v154
	ds_read_b128 v[184:187], v154 offset:0
	ds_read_b128 v[188:191], v154 offset:16
	ds_read_b128 v[192:195], v154 offset:128
	ds_read_b128 v[196:199], v154 offset:144
	ds_read_b128 v[200:203], v154 offset:256
	ds_read_b128 v[204:207], v154 offset:272
	ds_read_b128 v[208:211], v154 offset:384
	ds_read_b128 v[212:215], v154 offset:400
	s_lshl_b32 s0, s47, 5
	s_and_b32 s0, s0, 0xffffff00
	s_lshl_b32 s1, s50, 6
	s_add_i32 s28, s0, s1
	s_add_i32 s0, s51, s49
	s_mul_hi_u32 s1, s0, s85
	s_mul_i32 s0, s0, s85
	s_add_u32 s0, s0, s28
	s_addc_u32 s1, s1, 0
	s_add_u32 s0, s80, s0
	s_addc_u32 s1, s81, s1
	s_ashr_i32 s4, s49, 8
	s_mul_i32 s4, s4, 0x5800
	s_add_i32 s4, s4, s28
	s_add_u32 s6, s22, s4
	s_addc_u32 s7, s23, 0
	s_add_u32 s54, s82, s4
	s_addc_u32 s55, s83, 0
	s_sub_u32 s54, s54, 0x26800
	s_subb_u32 s55, s55, 0
	s_add_u32 s4, s20, s4
	s_addc_u32 s5, s21, 0
	v_mul_u32_u24_e32 v153, 0x2c00, v180
	v_lshl_add_u32 v153, v181, 4, v153
	v_and_b32_e32 v157, 1, v180
	v_lshlrev_b32_e32 v157, 5, v157
	v_lshl_add_u32 v157, v181, 6, v157
	s_lshl_b32 s62, s50, 8
	s_add_i32 s62, s62, 0x20000
	v_add_u32_e32 v157, s62, v157
	s_lshl_b32 s62, s34, 10
	v_add_u32_e32 v158, s62, v157
	s_add_i32 s62, s34, 3
	s_and_b32 s62, s62, 3
	s_lshl_b32 s62, s62, 10
	v_add_u32_e32 v159, s62, v157
	s_mov_b32 s52, 0xbdd2d3e8
	s_mov_b32 s53, 0xbdd2d3e8
	s_mov_b32 s94, 1.0
	s_mov_b32 s95, 1.0
	s_mov_b32 exec_lo, 0xc000c000
	s_mov_b32 exec_hi, 0xc000c000
	ds_write_b128 v158, v[100:103]
	ds_write_b128 v158, v[96:99] offset:16
	ds_write_b128 v158, v[4:7] offset:2048
	ds_write_b128 v158, v[0:3] offset:2064
	s_mov_b64 exec, -1
	s_waitcnt lgkmcnt(0)
	s_barrier
; DEV float bf2f(u16 h) { return __uint_as_float(((uint32_t)h) << 16); }
; DEV void gemm_tile(const u16* __restrict__ A, const u16* __restrict__ Bt, u16* __restrict__ C, int N, int K,
;                    int brow, int bcol, unsigned char* smem, int epi, const GateEpi& ge) {
;     ...
; #pragma unroll
;     for (int ai = 0; ai < 2; ++ai)
; #pragma unroll
;       for (int m = 0; m < 4; ++m) {
;         const int R0 = ai * 128 + wr * 64 + m * 16 + fq2 * 4;
; #pragma unroll
;         for (int n = 0; n < 2; ++n) {
;           const int cl = wc * 32 + n * 16 + fr2, cg = pn * 128 + cl;
;           float am2 = 0.f, am1 = 0.f;
;           if (R0 > 0) { am2 = bf2f(sAt[(R0 - 2) * AS + cl]); am1 = bf2f(sAt[(R0 - 1) * AS + cl]); }
; #pragma unroll
;           for (int j = 0; j < 4; ++j) {
;             const float a0 = acc[ai][0][m][n][j], b0 = acc[ai][1][m][n][j];
;             if (R0 > 0 || j >= 2) {
;               const float gv = gelu_tanh(bs[n] + w0[n] * am2 + w1[n] * am1 + w2[n] * a0) * b0;
;               ge.g[(size_t)(brow + R0 + j) * DFF + cg] = f2bf(gv);
;             } else {
;               ge.first_a[((size_t)pm * 2 + j) * DFF + cg] = sAt[(R0 + j) * AS + cl];
;               ge.first_b[((size_t)pm * 2 + j) * DFF + cg] = f2bf(b0);
;             }
;             if (R0 == 252 && j >= 2) ge.halo_a[((size_t)pm * 2 + (j - 2)) * DFF + cg] = sAt[(R0 + j) * AS + cl];
;             am2 = am1; am1 = a0;
;           }
;         }
;         __builtin_amdgcn_sched_barrier(0);
;       }
	ds_read_b128 v[232:235], v159
	ds_read_b128 v[236:239], v159 offset:16
	s_add_i32 s62, s34, 1
	s_lshl_b32 s62, s62, 10
	v_add_u32_e32 v156, s62, v157
	v_cmp_eq_u32_e32 vcc, 0, v180
	s_nop 1
	v_cndmask_b32_e32 v216, 0, v192, vcc
	v_cndmask_b32_e32 v217, 0, v193, vcc
	v_cndmask_b32_e32 v218, 0, v194, vcc
	v_cndmask_b32_e32 v219, 0, v195, vcc
	v_cndmask_b32_e32 v220, 0, v196, vcc
	v_cndmask_b32_e32 v221, 0, v197, vcc
	v_cndmask_b32_e32 v222, 0, v198, vcc
	v_cndmask_b32_e32 v223, 0, v199, vcc
	v_cmp_gt_u32_e32 vcc, 2, v180
	s_nop 1
	v_cndmask_b32_e32 v224, 0, v184, vcc
	v_cndmask_b32_e32 v225, 0, v185, vcc
	v_cndmask_b32_e32 v226, 0, v186, vcc
	v_cndmask_b32_e32 v227, 0, v187, vcc
	v_cndmask_b32_e32 v228, 0, v188, vcc
	v_cndmask_b32_e32 v229, 0, v189, vcc
	v_cndmask_b32_e32 v230, 0, v190, vcc
	v_cndmask_b32_e32 v231, 0, v191, vcc
	v_mov_b32_e32 v180, v163
	v_mov_b32_e32 v181, v163
	s_waitcnt lgkmcnt(0)
	v_pk_fma_f32 v[240:241], v[200:201], v[124:125], v[208:209]
	v_pk_fma_f32 v[242:243], v[202:203], v[126:127], v[210:211]
	v_pk_fma_f32 v[244:245], v[204:205], v[120:121], v[212:213]
	v_pk_fma_f32 v[246:247], v[206:207], v[122:123], v[214:215]
	v_fmac_f32_dpp v240, v124, v192 row_shr:1 row_mask:0xf bank_mask:0xf
	v_fmac_f32_dpp v241, v125, v193 row_shr:1 row_mask:0xf bank_mask:0xf
	v_fmac_f32_dpp v242, v126, v194 row_shr:1 row_mask:0xf bank_mask:0xf
	v_fmac_f32_dpp v243, v127, v195 row_shr:1 row_mask:0xf bank_mask:0xf
	v_fmac_f32_dpp v244, v120, v196 row_shr:1 row_mask:0xf bank_mask:0xf
	v_fmac_f32_dpp v245, v121, v197 row_shr:1 row_mask:0xf bank_mask:0xf
	v_fmac_f32_dpp v246, v122, v198 row_shr:1 row_mask:0xf bank_mask:0xf
	v_fmac_f32_dpp v247, v123, v199 row_shr:1 row_mask:0xf bank_mask:0xf
	v_fmac_f32_dpp v240, v232, v216 row_ror:1 row_mask:0xf bank_mask:0xf
	v_fmac_f32_dpp v241, v233, v217 row_ror:1 row_mask:0xf bank_mask:0xf
	v_fmac_f32_dpp v242, v234, v218 row_ror:1 row_mask:0xf bank_mask:0xf
	v_fmac_f32_dpp v243, v235, v219 row_ror:1 row_mask:0xf bank_mask:0xf
	v_fmac_f32_dpp v244, v236, v220 row_ror:1 row_mask:0xf bank_mask:0xf
	v_fmac_f32_dpp v245, v237, v221 row_ror:1 row_mask:0xf bank_mask:0xf
	v_fmac_f32_dpp v246, v238, v222 row_ror:1 row_mask:0xf bank_mask:0xf
	v_fmac_f32_dpp v247, v239, v223 row_ror:1 row_mask:0xf bank_mask:0xf
	v_fmac_f32_dpp v240, v124, v184 row_shr:2 row_mask:0xf bank_mask:0xf
	v_fmac_f32_dpp v241, v125, v185 row_shr:2 row_mask:0xf bank_mask:0xf
	v_fmac_f32_dpp v242, v126, v186 row_shr:2 row_mask:0xf bank_mask:0xf
	v_fmac_f32_dpp v243, v127, v187 row_shr:2 row_mask:0xf bank_mask:0xf
	v_fmac_f32_dpp v244, v120, v188 row_shr:2 row_mask:0xf bank_mask:0xf
	v_fmac_f32_dpp v245, v121, v189 row_shr:2 row_mask:0xf bank_mask:0xf
	v_fmac_f32_dpp v246, v122, v190 row_shr:2 row_mask:0xf bank_mask:0xf
	v_fmac_f32_dpp v247, v123, v191 row_shr:2 row_mask:0xf bank_mask:0xf
	v_fmac_f32_dpp v240, v232, v224 row_ror:2 row_mask:0xf bank_mask:0xf
	v_fmac_f32_dpp v241, v233, v225 row_ror:2 row_mask:0xf bank_mask:0xf
	v_fmac_f32_dpp v242, v234, v226 row_ror:2 row_mask:0xf bank_mask:0xf
	v_fmac_f32_dpp v243, v235, v227 row_ror:2 row_mask:0xf bank_mask:0xf
	v_fmac_f32_dpp v244, v236, v228 row_ror:2 row_mask:0xf bank_mask:0xf
	v_fmac_f32_dpp v245, v237, v229 row_ror:2 row_mask:0xf bank_mask:0xf
	v_fmac_f32_dpp v246, v238, v230 row_ror:2 row_mask:0xf bank_mask:0xf
	v_fmac_f32_dpp v247, v239, v231 row_ror:2 row_mask:0xf bank_mask:0xf
	ds_read_b128 v[232:235], v156
	ds_read_b128 v[236:239], v156 offset:16
	v_pk_mul_f32 v[248:249], v[240:241], v[240:241]
	v_pk_mul_f32 v[250:251], v[242:243], v[242:243]
	v_pk_mul_f32 v[182:183], v[244:245], v[244:245]
	v_pk_mul_f32 v[154:155], v[246:247], v[246:247]
	v_pk_fma_f32 v[248:249], v[248:249], s[52:53], v[180:181]
	v_pk_fma_f32 v[250:251], v[250:251], s[52:53], v[180:181]
	v_pk_fma_f32 v[182:183], v[182:183], s[52:53], v[180:181]
	v_pk_fma_f32 v[154:155], v[154:155], s[52:53], v[180:181]
	v_pk_mul_f32 v[248:249], v[240:241], v[248:249]
	v_pk_mul_f32 v[250:251], v[242:243], v[250:251]
	v_pk_mul_f32 v[182:183], v[244:245], v[182:183]
	v_pk_mul_f32 v[154:155], v[246:247], v[154:155]
	v_exp_f32_e32 v248, v248
	v_exp_f32_e32 v249, v249
	v_exp_f32_e32 v250, v250
	v_exp_f32_e32 v251, v251
	v_exp_f32_e32 v182, v182
	v_exp_f32_e32 v183, v183
	v_exp_f32_e32 v154, v154
	v_exp_f32_e32 v155, v155
	v_pk_add_f32 v[248:249], v[248:249], s[94:95]
	v_pk_add_f32 v[250:251], v[250:251], s[94:95]
	v_pk_add_f32 v[182:183], v[182:183], s[94:95]
	v_pk_add_f32 v[154:155], v[154:155], s[94:95]
	v_rcp_f32_e32 v248, v248
	v_rcp_f32_e32 v249, v249
	v_rcp_f32_e32 v250, v250
	v_rcp_f32_e32 v251, v251
	v_rcp_f32_e32 v182, v182
	v_rcp_f32_e32 v183, v183
	v_rcp_f32_e32 v154, v154
	v_rcp_f32_e32 v155, v155
	v_pk_mul_f32 v[240:241], v[240:241], v[248:249]
	v_pk_mul_f32 v[242:243], v[242:243], v[250:251]
	v_pk_mul_f32 v[244:245], v[244:245], v[182:183]
	v_pk_mul_f32 v[246:247], v[246:247], v[154:155]
	v_pk_mul_f32 v[240:241], v[240:241], v[84:85]
	v_pk_mul_f32 v[242:243], v[242:243], v[86:87]
	v_pk_mul_f32 v[244:245], v[244:245], v[68:69]
	v_pk_mul_f32 v[246:247], v[246:247], v[70:71]
	v_cvt_pk_bf16_f32 v248, v240, v241
	v_cvt_pk_bf16_f32 v249, v242, v243
	v_cvt_pk_bf16_f32 v250, v244, v245
	v_cvt_pk_bf16_f32 v251, v246, v247
	s_cmp_lg_u32 s34, 0
	s_cbranch_scc1 .Lgate_plain00_0
	s_mov_b32 exec_lo, 0x30003
	s_mov_b32 exec_hi, 0x30003
	v_cvt_pk_bf16_f32 v240, v124, v125
	v_cvt_pk_bf16_f32 v241, v126, v127
	v_cvt_pk_bf16_f32 v242, v120, v121
	v_cvt_pk_bf16_f32 v243, v122, v123
	v_cvt_pk_bf16_f32 v244, v84, v85
	v_cvt_pk_bf16_f32 v245, v86, v87
	v_cvt_pk_bf16_f32 v246, v68, v69
	v_cvt_pk_bf16_f32 v247, v70, v71
	global_store_dwordx4 v153, v[240:243], s[4:5]
	global_store_dwordx4 v153, v[244:247], s[6:7]
	s_not_b64 exec, exec
	global_store_dwordx4 v153, v[248:251], s[0:1]
	s_mov_b64 exec, -1
	s_branch .Lgate_done00_0

; #define STAGE(P, q) do { GLDS16(q[0], (unsigned char*)(P) + wid * 1024); GLDS16(q[1], (unsigned char*)(P) + wid * 1024 + 8192); \
;     q[0] += 128; q[1] += 128; asm volatile("" : "+v"(q[0]), "+v"(q[1])); } while (0)
; #define LDA(dst, b, h) _Pragma("unroll") for (int m = 0; m < 4; ++m) _Pragma("unroll") for (int k = 0; k < 2; ++k) \
;     dst[m][k] = *(const bf16x8*)((const unsigned char*)SA(b, h) + lds_byte1(wr * 64 + m * 16 + fr, k * 32 + fq * 8))
; #define LDB(dst, b, h) _Pragma("unroll") for (int n = 0; n < 2; ++n) _Pragma("unroll") for (int k = 0; k < 2; ++k) \
;     dst[n][k] = *(const bf16x8*)((const unsigned char*)SB(b, h) + lds_byte1(wc * 32 + n * 16 + fr, k * 32 + fq * 8))
; #define WAIT_V(n) asm volatile("s_waitcnt vmcnt(" #n ")" ::: "memory")
; #define WAIT_L(n) asm volatile("s_waitcnt lgkmcnt(" #n ")" ::: "memory")
; #define BAR __builtin_amdgcn_s_barrier()
; #define SCHED __builtin_amdgcn_sched_barrier(0)
; DEV void gemm_tile(const u16* __restrict__ A, const u16* __restrict__ Bt, u16* __restrict__ C, int N, int K,
;                    int brow, int bcol, unsigned char* smem, int epi, const GateEpi& ge) {
;     ...
;   f32x4 acc[2][2][4][2];
; #pragma unroll
;   for (int a = 0; a < 2; ++a)
; #pragma unroll
;     for (int b = 0; b < 2; ++b)
; #pragma unroll
;       for (int m = 0; m < 4; ++m)
; #pragma unroll
;         for (int n = 0; n < 2; ++n) acc[a][b][m][n] = (f32x4){0.f, 0.f, 0.f, 0.f};
;   bf16x8 At[4][2], B0[2][2], B1[2][2];
;   const int nt = K / 64;
;   WAIT_L(0);
;   __syncthreads();
;   STAGE(SB(0, 0), qB0); STAGE(SA(0, 0), qA0);
;   STAGE(SB(0, 1), qB1); STAGE(SA(0, 1), qA1);
;   if (wr == 1) BAR;
;   WAIT_V(4); BAR;
;   STAGE(SB(1, 0), qB0); STAGE(SA(1, 0), qA0); STAGE(SB(1, 1), qB1);
;   WAIT_V(6); BAR;
;   for (int t = 0; t < nt - 2; t += 2) {
;     LDB(B0, 0, 0); SCHED; LDA(At, 0, 0); STAGE(SA(1, 1), qA1);
;     WAIT_L(8); BAR; WAIT_L(0); MMA(0, 0, At, B0); BAR; SCHED;
; DEV void phase_gemm(const u16* A, const u16* Bt, u16* C, int ntiles, int N, int K, unsigned char* smem, int epi, const GateEpi& ge) {
;     ...
;   for (int t = lb; t < ntiles; t += gridDim.x) {
;     while (rem >= nig) { rem -= nig; ++gid; }
;     const int pm = gid * 8 + (rem & 7), pn = rem >> 3;
;     gemm_tile(A, Bt, C, N, K, pm * 256, pn * 256, smem, epi, ge);
;     rem += gridDim.x;
.Lgate_end_0:
.Lg_post:
	s_cmp_eq_u32 s63, 0
	s_cbranch_scc1 .LBB0_818
	s_add_i32 s48, s48, s33
	v_readlane_b32 s47, v252, 42
	v_readlane_b32 s46, v252, 43
	s_lshl_b32 s0, s47, 8
	s_and_b32 s0, s0, 0x700
	s_lshl_b32 s1, s46, 11
	s_or_b32 s49, s1, s0
	s_lshl_b32 s0, s47, 5
	s_and_b32 s92, s0, 0xffffff00
	s_ashr_i32 s93, s92, 31
	s_lshl_b32 s1, s34, 2
	s_add_i32 s1, s1, s50
	s_lshl_b32 s1, s1, 10
	s_add_i32 s56, s1, 0xc000
	s_add_i32 s52, s1, 0xe000
	s_add_i32 s4, s1, 0x10000
	s_add_i32 s5, s1, 0x12000
	s_add_i32 s6, s1, 0x2000
	s_add_i32 s7, s1, 0x14000
	s_add_i32 s35, s1, 0x16000
	s_add_i32 s41, s1, 0x4000
	s_add_i32 vcc_lo, s1, 0x6000
	s_add_i32 vcc_hi, s1, 0x18000
	s_add_i32 s28, s1, 0x1a000
	s_add_i32 s94, s1, 0x8000
	s_add_i32 s95, s1, 0xa000
	s_add_i32 s62, s1, 0x1c000
	s_add_i32 s63, s1, 0x1e000
	s_lshl_b32 s59, s34, 13
	s_or_b32 s53, s59, 0x800
	s_or_b32 s54, s59, 0x1000
	s_or_b32 s55, s59, 0x1800
	s_mov_b32 s57, 2
	s_andn2_b64 s[58:59], exec, s[2:3]
	s_cmp_lg_u64 s[58:59], 0
	s_cbranch_scc1 .Lg_nostag
	s_cmp_lg_u32 s34, 1
	s_cbranch_scc1 .Lg_nostag
	s_barrier
.Lg_nostag:
	ds_read_b128 v[156:159], v152
	ds_read_b128 v[180:183], v152 offset:1024
	ds_read_b128 v[184:187], v152 offset:256
	ds_read_b128 v[188:191], v152 offset:1280
	s_mov_b32 m0, s56
	v_add_u32_e32 v153, s53, v151
	v_add_u32_e32 v154, s54, v151
	v_add_u32_e32 v155, s55, v151
	ds_read_b128 v[192:195], v128
	ds_read_b128 v[196:199], v128 offset:1024
	ds_read_b128 v[200:203], v153
	ds_read_b128 v[204:207], v153 offset:1024
	ds_read_b128 v[208:211], v154
	ds_read_b128 v[212:215], v154 offset:1024
	ds_read_b128 v[216:219], v155
	ds_read_b128 v[220:223], v155 offset:1024
	global_load_lds_dwordx4 v[132:133], off
	s_mov_b32 m0, s52
	v_lshl_add_u64 v[236:237], v[132:133], 0, s[8:9]
	global_load_lds_dwordx4 v[134:135], off
	v_lshl_add_u64 v[238:239], v[134:135], 0, s[8:9]
	s_waitcnt lgkmcnt(8)
	s_barrier
	s_waitcnt lgkmcnt(0)
	s_setprio 1
	s_waitcnt lgkmcnt(0)
	v_mfma_f32_16x16x32_bf16 v[124:127], v[156:159], v[192:195], 0
	v_mfma_f32_16x16x32_bf16 v[120:123], v[184:187], v[192:195], 0
	v_mfma_f32_16x16x32_bf16 v[116:119], v[156:159], v[200:203], 0
	v_mfma_f32_16x16x32_bf16 v[112:115], v[184:187], v[200:203], 0
	v_mfma_f32_16x16x32_bf16 v[108:111], v[156:159], v[208:211], 0
	v_mfma_f32_16x16x32_bf16 v[104:107], v[184:187], v[208:211], 0
	v_mfma_f32_16x16x32_bf16 v[100:103], v[156:159], v[216:219], 0
	v_mfma_f32_16x16x32_bf16 v[96:99], v[184:187], v[216:219], 0
	v_mfma_f32_16x16x32_bf16 v[124:127], v[180:183], v[196:199], v[124:127]
	v_mfma_f32_16x16x32_bf16 v[120:123], v[188:191], v[196:199], v[120:123]
	v_mfma_f32_16x16x32_bf16 v[116:119], v[180:183], v[204:207], v[116:119]
	v_mfma_f32_16x16x32_bf16 v[112:115], v[188:191], v[204:207], v[112:115]
	v_mfma_f32_16x16x32_bf16 v[108:111], v[180:183], v[212:215], v[108:111]
	v_mfma_f32_16x16x32_bf16 v[104:107], v[188:191], v[212:215], v[104:107]
	v_mfma_f32_16x16x32_bf16 v[100:103], v[180:183], v[220:223], v[100:103]
	v_mfma_f32_16x16x32_bf16 v[96:99], v[188:191], v[220:223], v[96:99]
	s_setprio 0
	s_barrier
	s_mov_b32 m0, s4
	ds_read_b128 v[132:135], v150
	ds_read_b128 v[224:227], v150 offset:1024
	ds_read_b128 v[228:231], v150 offset:256
	ds_read_b128 v[232:235], v150 offset:1280
	global_load_lds_dwordx4 v[136:137], off
	s_mov_b32 m0, s5
	v_lshl_add_u64 v[240:241], v[136:137], 0, s[8:9]
	global_load_lds_dwordx4 v[138:139], off
	v_lshl_add_u64 v[242:243], v[138:139], 0, s[8:9]
	s_barrier
	s_waitcnt lgkmcnt(0)
	s_setprio 1
	s_waitcnt lgkmcnt(0)
	v_mfma_f32_16x16x32_bf16 v[84:87], v[132:135], v[192:195], 0
	v_mfma_f32_16x16x32_bf16 v[68:71], v[228:231], v[192:195], 0
	v_mfma_f32_16x16x32_bf16 v[52:55], v[132:135], v[200:203], 0
	v_mfma_f32_16x16x32_bf16 v[48:51], v[228:231], v[200:203], 0
	v_mfma_f32_16x16x32_bf16 v[44:47], v[132:135], v[208:211], 0
	v_mfma_f32_16x16x32_bf16 v[40:43], v[228:231], v[208:211], 0
	v_mfma_f32_16x16x32_bf16 v[36:39], v[132:135], v[216:219], 0
	v_mfma_f32_16x16x32_bf16 v[32:35], v[228:231], v[216:219], 0
	v_mfma_f32_16x16x32_bf16 v[84:87], v[224:227], v[196:199], v[84:87]
	v_mfma_f32_16x16x32_bf16 v[68:71], v[232:235], v[196:199], v[68:71]
	v_mfma_f32_16x16x32_bf16 v[52:55], v[224:227], v[204:207], v[52:55]
	v_mfma_f32_16x16x32_bf16 v[48:51], v[232:235], v[204:207], v[48:51]
	v_mfma_f32_16x16x32_bf16 v[44:47], v[224:227], v[212:215], v[44:47]
	v_mfma_f32_16x16x32_bf16 v[40:43], v[232:235], v[212:215], v[40:43]
	v_mfma_f32_16x16x32_bf16 v[36:39], v[224:227], v[220:223], v[36:39]
	v_mfma_f32_16x16x32_bf16 v[32:35], v[232:235], v[220:223], v[32:35]
	s_setprio 0
	s_mov_b32 m0, s1
	s_barrier
	ds_read_b128 v[136:139], v128 offset:16384
	ds_read_b128 v[192:195], v128 offset:17408
	ds_read_b128 v[196:199], v153 offset:16384
	ds_read_b128 v[200:203], v153 offset:17408
	ds_read_b128 v[204:207], v154 offset:16384
	ds_read_b128 v[208:211], v154 offset:17408
	ds_read_b128 v[212:215], v155 offset:16384
	ds_read_b128 v[216:219], v155 offset:17408
	global_load_lds_dwordx4 v[140:141], off
	s_mov_b32 m0, s6
	v_lshl_add_u64 v[244:245], v[140:141], 0, s[8:9]
	global_load_lds_dwordx4 v[142:143], off
	v_lshl_add_u64 v[246:247], v[142:143], 0, s[8:9]
	s_barrier
; #define STAGE(P, q) do { GLDS16(q[0], (unsigned char*)(P) + wid * 1024); GLDS16(q[1], (unsigned char*)(P) + wid * 1024 + 8192); \
;     q[0] += 128; q[1] += 128; asm volatile("" : "+v"(q[0]), "+v"(q[1])); } while (0)
; #define LDA(dst, b, h) _Pragma("unroll") for (int m = 0; m < 4; ++m) _Pragma("unroll") for (int k = 0; k < 2; ++k) \
;     dst[m][k] = *(const bf16x8*)((const unsigned char*)SA(b, h) + lds_byte1(wr * 64 + m * 16 + fr, k * 32 + fq * 8))
; #define LDB(dst, b, h) _Pragma("unroll") for (int n = 0; n < 2; ++n) _Pragma("unroll") for (int k = 0; k < 2; ++k) \
;     dst[n][k] = *(const bf16x8*)((const unsigned char*)SB(b, h) + lds_byte1(wc * 32 + n * 16 + fr, k * 32 + fq * 8))
; #define MMA(ai, bj, At_, Bt_) do { __builtin_amdgcn_s_setprio(1); \
;     _Pragma("unroll") for (int m = 0; m < 4; ++m) _Pragma("unroll") for (int n = 0; n < 2; ++n) _Pragma("unroll") for (int k = 0; k < 2; ++k) \
;       acc[ai][bj][m][n] = mfma16(At_[m][k], Bt_[n][k], acc[ai][bj][m][n]); \
;     __builtin_amdgcn_s_setprio(0); } while (0)
; #define WAIT_V(n) asm volatile("s_waitcnt vmcnt(" #n ")" ::: "memory")
; #define WAIT_L(n) asm volatile("s_waitcnt lgkmcnt(" #n ")" ::: "memory")
; #define BAR __builtin_amdgcn_s_barrier()
; #define SCHED __builtin_amdgcn_sched_barrier(0)
; DEV void gemm_tile(const u16* __restrict__ A, const u16* __restrict__ Bt, u16* __restrict__ C, int N, int K,
;                    int brow, int bcol, unsigned char* smem, int epi, const GateEpi& ge) {
;     ...
;   for (int t = 0; t < nt - 2; t += 2) {
;     LDB(B0, 0, 0); SCHED; LDA(At, 0, 0); STAGE(SA(1, 1), qA1);
;     WAIT_L(8); BAR; WAIT_L(0); MMA(0, 0, At, B0); BAR; SCHED;
;     LDB(B1, 0, 1); STAGE(SB(0, 0), qB0);
;     BAR; WAIT_L(0); MMA(0, 1, At, B1); BAR;
;     LDA(At, 0, 1); STAGE(SA(0, 0), qA0);
;     BAR; WAIT_L(0); MMA(1, 0, At, B0); BAR; SCHED;
;     STAGE(SB(0, 1), qB1);
;     WAIT_V(6); BAR; MMA(1, 1, At, B1); BAR;
;     LDB(B0, 1, 0); SCHED; LDA(At, 1, 0); STAGE(SA(0, 1), qA1);
;     WAIT_L(8); BAR; WAIT_L(0); MMA(0, 0, At, B0); BAR; SCHED;
	s_waitcnt lgkmcnt(0)
	s_setprio 1
	s_waitcnt lgkmcnt(0)
	v_mfma_f32_16x16x32_bf16 v[28:31], v[156:159], v[136:139], 0
	v_mfma_f32_16x16x32_bf16 v[24:27], v[184:187], v[136:139], 0
	v_mfma_f32_16x16x32_bf16 v[20:23], v[156:159], v[196:199], 0
	v_mfma_f32_16x16x32_bf16 v[16:19], v[184:187], v[196:199], 0
	v_mfma_f32_16x16x32_bf16 v[12:15], v[156:159], v[204:207], 0
	v_mfma_f32_16x16x32_bf16 v[8:11], v[184:187], v[204:207], 0
	v_mfma_f32_16x16x32_bf16 v[4:7], v[156:159], v[212:215], 0
	v_mfma_f32_16x16x32_bf16 v[0:3], v[184:187], v[212:215], 0
	v_mfma_f32_16x16x32_bf16 v[28:31], v[180:183], v[192:195], v[28:31]
	v_mfma_f32_16x16x32_bf16 v[24:27], v[188:191], v[192:195], v[24:27]
	v_mfma_f32_16x16x32_bf16 v[20:23], v[180:183], v[200:203], v[20:23]
	v_mfma_f32_16x16x32_bf16 v[16:19], v[188:191], v[200:203], v[16:19]
	v_mfma_f32_16x16x32_bf16 v[12:15], v[180:183], v[208:211], v[12:15]
	v_mfma_f32_16x16x32_bf16 v[8:11], v[188:191], v[208:211], v[8:11]
	v_mfma_f32_16x16x32_bf16 v[4:7], v[180:183], v[216:219], v[4:7]
	v_mfma_f32_16x16x32_bf16 v[0:3], v[188:191], v[216:219], v[0:3]
	s_setprio 0
	s_barrier
	s_mov_b32 m0, s7
	v_lshl_add_u64 v[248:249], v[144:145], 0, s[8:9]
	global_load_lds_dwordx4 v[144:145], off
	s_mov_b32 m0, s35
	v_lshl_add_u64 v[250:251], v[146:147], 0, s[8:9]
	global_load_lds_dwordx4 v[146:147], off
	s_waitcnt vmcnt(6)
	s_barrier
	s_setprio 1
	v_mfma_f32_16x16x32_bf16 v[56:59], v[132:135], v[136:139], 0
	v_mfma_f32_16x16x32_bf16 v[60:63], v[228:231], v[136:139], 0
	v_mfma_f32_16x16x32_bf16 v[64:67], v[132:135], v[196:199], 0
	v_mfma_f32_16x16x32_bf16 v[72:75], v[228:231], v[196:199], 0
	v_mfma_f32_16x16x32_bf16 v[76:79], v[132:135], v[204:207], 0
	v_mfma_f32_16x16x32_bf16 v[80:83], v[228:231], v[204:207], 0
	v_mfma_f32_16x16x32_bf16 v[88:91], v[132:135], v[212:215], 0
	v_mfma_f32_16x16x32_bf16 v[92:95], v[228:231], v[212:215], 0
	v_mfma_f32_16x16x32_bf16 v[56:59], v[224:227], v[192:195], v[56:59]
	v_mfma_f32_16x16x32_bf16 v[60:63], v[232:235], v[192:195], v[60:63]
	v_mfma_f32_16x16x32_bf16 v[64:67], v[224:227], v[200:203], v[64:67]
	v_mfma_f32_16x16x32_bf16 v[72:75], v[232:235], v[200:203], v[72:75]
	v_mfma_f32_16x16x32_bf16 v[76:79], v[224:227], v[208:211], v[76:79]
	v_mfma_f32_16x16x32_bf16 v[80:83], v[232:235], v[208:211], v[80:83]
	v_mfma_f32_16x16x32_bf16 v[88:91], v[224:227], v[216:219], v[88:91]
	v_mfma_f32_16x16x32_bf16 v[92:95], v[232:235], v[216:219], v[92:95]
	s_setprio 0
	s_barrier
	ds_read_b128 v[144:147], v149
	ds_read_b128 v[156:159], v149 offset:1024
	ds_read_b128 v[180:183], v149 offset:256
	ds_read_b128 v[184:187], v149 offset:1280
	s_mov_b32 m0, s41
	ds_read_b128 v[140:143], v128 offset:32768
	ds_read_b128 v[188:191], v128 offset:33792
	ds_read_b128 v[192:195], v153 offset:32768
	ds_read_b128 v[196:199], v153 offset:33792
	ds_read_b128 v[200:203], v154 offset:32768
	ds_read_b128 v[204:207], v154 offset:33792
	ds_read_b128 v[208:211], v155 offset:32768
	ds_read_b128 v[212:215], v155 offset:33792
	global_load_lds_dwordx4 v[236:237], off
	s_mov_b32 m0, vcc_lo
	v_lshl_add_u64 v[132:133], v[236:237], 0, s[8:9]
	global_load_lds_dwordx4 v[238:239], off
	v_lshl_add_u64 v[134:135], v[238:239], 0, s[8:9]
	s_waitcnt lgkmcnt(8)
	s_barrier
	s_waitcnt lgkmcnt(0)
	s_setprio 1
	s_waitcnt lgkmcnt(0)
	v_mfma_f32_16x16x32_bf16 v[124:127], v[144:147], v[140:143], v[124:127]
	v_mfma_f32_16x16x32_bf16 v[120:123], v[180:183], v[140:143], v[120:123]
	v_mfma_f32_16x16x32_bf16 v[116:119], v[144:147], v[192:195], v[116:119]
	v_mfma_f32_16x16x32_bf16 v[112:115], v[180:183], v[192:195], v[112:115]
	v_mfma_f32_16x16x32_bf16 v[108:111], v[144:147], v[200:203], v[108:111]
	v_mfma_f32_16x16x32_bf16 v[104:107], v[180:183], v[200:203], v[104:107]
	v_mfma_f32_16x16x32_bf16 v[100:103], v[144:147], v[208:211], v[100:103]
	v_mfma_f32_16x16x32_bf16 v[96:99], v[180:183], v[208:211], v[96:99]
	v_mfma_f32_16x16x32_bf16 v[124:127], v[156:159], v[188:191], v[124:127]
	v_mfma_f32_16x16x32_bf16 v[120:123], v[184:187], v[188:191], v[120:123]
	v_mfma_f32_16x16x32_bf16 v[116:119], v[156:159], v[196:199], v[116:119]
	v_mfma_f32_16x16x32_bf16 v[112:115], v[184:187], v[196:199], v[112:115]
	v_mfma_f32_16x16x32_bf16 v[108:111], v[156:159], v[204:207], v[108:111]
	v_mfma_f32_16x16x32_bf16 v[104:107], v[184:187], v[204:207], v[104:107]
	v_mfma_f32_16x16x32_bf16 v[100:103], v[156:159], v[212:215], v[100:103]
	v_mfma_f32_16x16x32_bf16 v[96:99], v[184:187], v[212:215], v[96:99]
	s_setprio 0
	s_barrier
; #define STAGE(P, q) do { GLDS16(q[0], (unsigned char*)(P) + wid * 1024); GLDS16(q[1], (unsigned char*)(P) + wid * 1024 + 8192); \
;     q[0] += 128; q[1] += 128; asm volatile("" : "+v"(q[0]), "+v"(q[1])); } while (0)
; #define LDA(dst, b, h) _Pragma("unroll") for (int m = 0; m < 4; ++m) _Pragma("unroll") for (int k = 0; k < 2; ++k) \
;     dst[m][k] = *(const bf16x8*)((const unsigned char*)SA(b, h) + lds_byte1(wr * 64 + m * 16 + fr, k * 32 + fq * 8))
; #define LDB(dst, b, h) _Pragma("unroll") for (int n = 0; n < 2; ++n) _Pragma("unroll") for (int k = 0; k < 2; ++k) \
;     dst[n][k] = *(const bf16x8*)((const unsigned char*)SB(b, h) + lds_byte1(wc * 32 + n * 16 + fr, k * 32 + fq * 8))
; #define MMA(ai, bj, At_, Bt_) do { __builtin_amdgcn_s_setprio(1); \
;     _Pragma("unroll") for (int m = 0; m < 4; ++m) _Pragma("unroll") for (int n = 0; n < 2; ++n) _Pragma("unroll") for (int k = 0; k < 2; ++k) \
;       acc[ai][bj][m][n] = mfma16(At_[m][k], Bt_[n][k], acc[ai][bj][m][n]); \
;     __builtin_amdgcn_s_setprio(0); } while (0)
; #define WAIT_V(n) asm volatile("s_waitcnt vmcnt(" #n ")" ::: "memory")
; #define WAIT_L(n) asm volatile("s_waitcnt lgkmcnt(" #n ")" ::: "memory")
; #define BAR __builtin_amdgcn_s_barrier()
; #define SCHED __builtin_amdgcn_sched_barrier(0)
; DEV void gemm_tile(const u16* __restrict__ A, const u16* __restrict__ Bt, u16* __restrict__ C, int N, int K,
;                    int brow, int bcol, unsigned char* smem, int epi, const GateEpi& ge) {
;     ...
;     WAIT_V(6); BAR; MMA(1, 1, At, B1); BAR;
;     LDB(B0, 1, 0); SCHED; LDA(At, 1, 0); STAGE(SA(0, 1), qA1);
;     WAIT_L(8); BAR; WAIT_L(0); MMA(0, 0, At, B0); BAR; SCHED;
;     LDB(B1, 1, 1); STAGE(SB(1, 0), qB0);
;     BAR; WAIT_L(0); MMA(0, 1, At, B1); BAR;
;     LDA(At, 1, 1); STAGE(SA(1, 0), qA0);
;     BAR; WAIT_L(0); MMA(1, 0, At, B0); BAR; SCHED;
;     STAGE(SB(1, 1), qB1);
;     WAIT_V(6); BAR; MMA(1, 1, At, B1); BAR;
;   }
	s_mov_b32 m0, vcc_hi
	ds_read_b128 v[216:219], v148
	ds_read_b128 v[220:223], v148 offset:1024
	ds_read_b128 v[224:227], v148 offset:256
	ds_read_b128 v[228:231], v148 offset:1280
	global_load_lds_dwordx4 v[240:241], off
	s_mov_b32 m0, s28
	v_lshl_add_u64 v[136:137], v[240:241], 0, s[8:9]
	global_load_lds_dwordx4 v[242:243], off
	v_lshl_add_u64 v[138:139], v[242:243], 0, s[8:9]
	s_barrier
	s_waitcnt lgkmcnt(0)
	s_setprio 1
	s_waitcnt lgkmcnt(0)
	v_mfma_f32_16x16x32_bf16 v[84:87], v[216:219], v[140:143], v[84:87]
	v_mfma_f32_16x16x32_bf16 v[68:71], v[224:227], v[140:143], v[68:71]
	v_mfma_f32_16x16x32_bf16 v[52:55], v[216:219], v[192:195], v[52:55]
	v_mfma_f32_16x16x32_bf16 v[48:51], v[224:227], v[192:195], v[48:51]
	v_mfma_f32_16x16x32_bf16 v[44:47], v[216:219], v[200:203], v[44:47]
	v_mfma_f32_16x16x32_bf16 v[40:43], v[224:227], v[200:203], v[40:43]
	v_mfma_f32_16x16x32_bf16 v[36:39], v[216:219], v[208:211], v[36:39]
	v_mfma_f32_16x16x32_bf16 v[32:35], v[224:227], v[208:211], v[32:35]
	v_mfma_f32_16x16x32_bf16 v[84:87], v[220:223], v[188:191], v[84:87]
	v_mfma_f32_16x16x32_bf16 v[68:71], v[228:231], v[188:191], v[68:71]
	v_mfma_f32_16x16x32_bf16 v[52:55], v[220:223], v[196:199], v[52:55]
	v_mfma_f32_16x16x32_bf16 v[48:51], v[228:231], v[196:199], v[48:51]
	v_mfma_f32_16x16x32_bf16 v[44:47], v[220:223], v[204:207], v[44:47]
	v_mfma_f32_16x16x32_bf16 v[40:43], v[228:231], v[204:207], v[40:43]
	v_mfma_f32_16x16x32_bf16 v[36:39], v[220:223], v[212:215], v[36:39]
	v_mfma_f32_16x16x32_bf16 v[32:35], v[228:231], v[212:215], v[32:35]
	s_setprio 0
	s_mov_b32 m0, s94
	s_barrier
	ds_read_b128 v[188:191], v128 offset:49152
	ds_read_b128 v[192:195], v128 offset:50176
	ds_read_b128 v[196:199], v153 offset:49152
	ds_read_b128 v[200:203], v153 offset:50176
	ds_read_b128 v[204:207], v154 offset:49152
	ds_read_b128 v[208:211], v154 offset:50176
	ds_read_b128 v[212:215], v155 offset:49152
	ds_read_b128 v[232:235], v155 offset:50176
	global_load_lds_dwordx4 v[244:245], off
	s_mov_b32 m0, s95
	v_lshl_add_u64 v[140:141], v[244:245], 0, s[8:9]
	global_load_lds_dwordx4 v[246:247], off
	v_lshl_add_u64 v[142:143], v[246:247], 0, s[8:9]
	s_barrier
	s_waitcnt lgkmcnt(0)
	s_setprio 1
	s_waitcnt lgkmcnt(0)
	v_mfma_f32_16x16x32_bf16 v[28:31], v[144:147], v[188:191], v[28:31]
	v_mfma_f32_16x16x32_bf16 v[24:27], v[180:183], v[188:191], v[24:27]
	v_mfma_f32_16x16x32_bf16 v[20:23], v[144:147], v[196:199], v[20:23]
	v_mfma_f32_16x16x32_bf16 v[16:19], v[180:183], v[196:199], v[16:19]
	v_mfma_f32_16x16x32_bf16 v[12:15], v[144:147], v[204:207], v[12:15]
	v_mfma_f32_16x16x32_bf16 v[8:11], v[180:183], v[204:207], v[8:11]
	v_mfma_f32_16x16x32_bf16 v[4:7], v[144:147], v[212:215], v[4:7]
	v_mfma_f32_16x16x32_bf16 v[0:3], v[180:183], v[212:215], v[0:3]
	v_mfma_f32_16x16x32_bf16 v[28:31], v[156:159], v[192:195], v[28:31]
	v_mfma_f32_16x16x32_bf16 v[24:27], v[184:187], v[192:195], v[24:27]
	v_mfma_f32_16x16x32_bf16 v[20:23], v[156:159], v[200:203], v[20:23]
	v_mfma_f32_16x16x32_bf16 v[16:19], v[184:187], v[200:203], v[16:19]
	v_mfma_f32_16x16x32_bf16 v[12:15], v[156:159], v[208:211], v[12:15]
	v_mfma_f32_16x16x32_bf16 v[8:11], v[184:187], v[208:211], v[8:11]
	v_mfma_f32_16x16x32_bf16 v[4:7], v[156:159], v[232:235], v[4:7]
	v_mfma_f32_16x16x32_bf16 v[0:3], v[184:187], v[232:235], v[0:3]
	s_setprio 0
	s_barrier
	s_mov_b32 m0, s62
	v_lshl_add_u64 v[144:145], v[248:249], 0, s[8:9]
	global_load_lds_dwordx4 v[248:249], off
	s_mov_b32 m0, s63
	v_lshl_add_u64 v[146:147], v[250:251], 0, s[8:9]
	global_load_lds_dwordx4 v[250:251], off
	s_waitcnt vmcnt(6)
	s_barrier
	s_setprio 1
	v_mfma_f32_16x16x32_bf16 v[56:59], v[216:219], v[188:191], v[56:59]
	v_mfma_f32_16x16x32_bf16 v[60:63], v[224:227], v[188:191], v[60:63]
	v_mfma_f32_16x16x32_bf16 v[64:67], v[216:219], v[196:199], v[64:67]
	v_mfma_f32_16x16x32_bf16 v[72:75], v[224:227], v[196:199], v[72:75]
	v_mfma_f32_16x16x32_bf16 v[76:79], v[216:219], v[204:207], v[76:79]
	v_mfma_f32_16x16x32_bf16 v[80:83], v[224:227], v[204:207], v[80:83]
	v_mfma_f32_16x16x32_bf16 v[88:91], v[216:219], v[212:215], v[88:91]
	v_mfma_f32_16x16x32_bf16 v[92:95], v[224:227], v[212:215], v[92:95]
	v_mfma_f32_16x16x32_bf16 v[56:59], v[220:223], v[192:195], v[56:59]
	v_mfma_f32_16x16x32_bf16 v[60:63], v[228:231], v[192:195], v[60:63]
	v_mfma_f32_16x16x32_bf16 v[64:67], v[220:223], v[200:203], v[64:67]
	v_mfma_f32_16x16x32_bf16 v[72:75], v[228:231], v[200:203], v[72:75]
	v_mfma_f32_16x16x32_bf16 v[76:79], v[220:223], v[208:211], v[76:79]
	v_mfma_f32_16x16x32_bf16 v[80:83], v[228:231], v[208:211], v[80:83]
	v_mfma_f32_16x16x32_bf16 v[88:91], v[220:223], v[232:235], v[88:91]
	v_mfma_f32_16x16x32_bf16 v[92:95], v[228:231], v[232:235], v[92:95]
	s_setprio 0
	s_barrier
	s_branch .LBB0_634

; __global__ void __launch_bounds__(NT, 2) k_mega(Params p) {
;   __shared__ __attribute__((aligned(1024))) unsigned char smem[LDS_BYTES];
	.amdhsa_kernel _Z6k_mega6Params
		.amdhsa_group_segment_fixed_size 143360
		.amdhsa_private_segment_fixed_size 0
		.amdhsa_kernarg_size 504
		.amdhsa_user_sgpr_count 2
		.amdhsa_user_sgpr_dispatch_ptr 0
		.amdhsa_user_sgpr_queue_ptr 0
		.amdhsa_user_sgpr_kernarg_segment_ptr 1
		.amdhsa_user_sgpr_dispatch_id 0
		.amdhsa_user_sgpr_kernarg_preload_length 0
		.amdhsa_user_sgpr_kernarg_preload_offset 0
		.amdhsa_user_sgpr_private_segment_size 0
		.amdhsa_uses_dynamic_stack 0
		.amdhsa_enable_private_segment 0
		.amdhsa_system_sgpr_workgroup_id_x 1
		.amdhsa_system_sgpr_workgroup_id_y 0
		.amdhsa_system_sgpr_workgroup_id_z 0
		.amdhsa_system_sgpr_workgroup_info 0
		.amdhsa_system_vgpr_workitem_id 2
		.amdhsa_next_free_vgpr 254
		.amdhsa_next_free_sgpr 100
		.amdhsa_accum_offset 256
		.amdhsa_reserve_vcc 1
		.amdhsa_float_round_mode_32 0
		.amdhsa_float_round_mode_16_64 0
		.amdhsa_float_denorm_mode_32 3
		.amdhsa_float_denorm_mode_16_64 3
		.amdhsa_dx10_clamp 1
		.amdhsa_ieee_mode 1
		.amdhsa_fp16_overflow 0
		.amdhsa_tg_split 0
		.amdhsa_exception_fp_ieee_invalid_op 0
		.amdhsa_exception_fp_denorm_src 0
		.amdhsa_exception_fp_ieee_div_zero 0
		.amdhsa_exception_fp_ieee_overflow 0
		.amdhsa_exception_fp_ieee_underflow 0
		.amdhsa_exception_fp_ieee_inexact 0
		.amdhsa_exception_int_div_zero 0
	.end_amdhsa_kernel

; __global__ void __launch_bounds__(NT, 2) k_mega(Params p) {
;   __shared__ __attribute__((aligned(1024))) unsigned char smem[LDS_BYTES];
amdhsa.kernels:
  - .agpr_count:     0
    .args:
      - .offset:         0
        .size:           248
        .value_kind:     by_value
      - .offset:         248
        .size:           4
        .value_kind:     hidden_block_count_x
      - .offset:         252
        .size:           4
        .value_kind:     hidden_block_count_y
      - .offset:         256
        .size:           4
        .value_kind:     hidden_block_count_z
      - .offset:         260
        .size:           2
        .value_kind:     hidden_group_size_x
      - .offset:         262
        .size:           2
        .value_kind:     hidden_group_size_y
      - .offset:         264
        .size:           2
        .value_kind:     hidden_group_size_z
      - .offset:         266
        .size:           2
        .value_kind:     hidden_remainder_x
      - .offset:         268
        .size:           2
        .value_kind:     hidden_remainder_y
      - .offset:         270
        .size:           2
        .value_kind:     hidden_remainder_z
      - .offset:         288
        .size:           8
        .value_kind:     hidden_global_offset_x
      - .offset:         296
        .size:           8
        .value_kind:     hidden_global_offset_y
      - .offset:         304
        .size:           8
        .value_kind:     hidden_global_offset_z
      - .offset:         312
        .size:           2
        .value_kind:     hidden_grid_dims
      - .offset:         336
        .size:           8
        .value_kind:     hidden_multigrid_sync_arg
    .group_segment_fixed_size: 143360
    .kernarg_segment_align: 8
    .kernarg_segment_size: 504
    .language:       OpenCL C
    .language_version:
      - 2
      - 0
    .max_flat_workgroup_size: 512
    .name:           _Z6k_mega6Params
    .private_segment_fixed_size: 0
    .sgpr_count:     106
    .sgpr_spill_count: 107
    .symbol:         _Z6k_mega6Params.kd
    .uniform_work_group_size: 1
    .uses_dynamic_stack: false
    .vgpr_count:     254
    .vgpr_spill_count: 0
    .wavefront_size: 64
